# v033 + write-through (sc1) for the P0 conversion stores (bf16 weights, hb)
# speedup vs baseline: 1.0056x; 1.0056x over previous
; #define LAS __attribute__((address_space(3)))
; __device__ __forceinline__ unsigned cvt_pk_bf16(float lo, float hi) { unsigned r; asm("v_cvt_pk_bf16_f32 %0, %1, %2" : "=v"(r) : "v"(lo), "v"(hi)); return r; }
; template <int MAPK>
; __device__ __forceinline__ void transpose_item(const float* W, int K, int N, int ND, bf16_t* WT, const float* g, LAS float* scr, int item, int lane) {
;     ...
;     for (int i = 0; i < 16; ++i) { const int kk = 4 * i + kr; f32x4 v = vv[i];
;         if (g) v = v * g[k0 + kk];
;         scr[kk * 65 + c4] = v[0]; scr[kk * 65 + c4 + 1] = v[1]; scr[kk * 65 + c4 + 2] = v[2]; scr[kk * 65 + c4 + 3] = v[3]; }
;     asm volatile("s_waitcnt lgkmcnt(0)" ::: "memory");
;     const int c = lane & 7;
; #pragma unroll
;     for (int j = 0; j < 8; ++j) { const int n = (lane >> 3) + 8 * j; const LAS float* sp = scr + (8 * c) * 65 + n;
;         u32x4 o; o.x = cvt_pk_bf16(sp[0], sp[65]); o.y = cvt_pk_bf16(sp[2 * 65], sp[3 * 65]); o.z = cvt_pk_bf16(sp[4 * 65], sp[5 * 65]); o.w = cvt_pk_bf16(sp[6 * 65], sp[7 * 65]);
;         *(u32x4*)(WT + (size_t)(n0 + n) * K + k0 + 8 * c) = o; }
;     asm volatile("s_waitcnt lgkmcnt(0)" ::: "memory");
.LBB0_21:
	v_add_u32_e32 v4, 0x1040, v0
	ds_write2_b32 v4, v16, v17 offset1:1
	v_add_u32_e32 v4, 0x1048, v0
	ds_write2_b32 v4, v2, v3 offset1:1
	v_add_u32_e32 v2, 0x1450, v0
	v_add_u32_e32 v0, 0x1458, v0
	ds_write2_b32 v2, v12, v13 offset1:1
	ds_write2_b32 v0, v14, v15 offset1:1
	s_waitcnt lgkmcnt(0)
	ds_read_b32 v0, v85
	ds_read_b32 v2, v85 offset:260
	ds_read_b32 v3, v85 offset:520
	ds_read_b32 v4, v85 offset:780
	ds_read_b32 v5, v85 offset:1040
	ds_read_b32 v8, v85 offset:1300
	ds_read_b32 v9, v85 offset:1560
	ds_read_b32 v10, v85 offset:1820
	s_add_u32 s18, s7, s91
	s_addc_u32 s19, s9, s90
	s_lshl_b64 s[0:1], s[20:21], 1
	s_add_u32 s0, s18, s0
	s_waitcnt lgkmcnt(0)
	v_cvt_pk_bf16_f32 v3, v3, v4
	v_cvt_pk_bf16_f32 v4, v5, v8
	v_or_b32_e32 v8, s92, v84
	s_addc_u32 s1, s19, s1
	v_mov_b32_e32 v79, v1
	v_cvt_pk_bf16_f32 v5, v9, v10
	v_ashrrev_i32_e32 v9, 31, v8
	v_lshl_add_u64 v[6:7], s[0:1], 0, v[78:79]
	v_lshlrev_b64 v[8:9], 12, v[8:9]
	v_lshl_add_u64 v[8:9], v[6:7], 0, v[8:9]
	v_cvt_pk_bf16_f32 v2, v0, v2
	flat_store_dwordx4 v[8:9], v[2:5] sc1
	ds_read_b32 v0, v85 offset:32
	ds_read_b32 v2, v85 offset:292
	ds_read_b32 v3, v85 offset:552
	ds_read_b32 v4, v85 offset:812
	ds_read_b32 v5, v85 offset:1072
	ds_read_b32 v8, v85 offset:1332
	ds_read_b32 v9, v85 offset:1592
	ds_read_b32 v10, v85 offset:1852
	s_waitcnt lgkmcnt(0)
	v_cvt_pk_bf16_f32 v3, v3, v4
	v_cvt_pk_bf16_f32 v4, v5, v8
	v_or_b32_e32 v8, s92, v86
	v_cvt_pk_bf16_f32 v5, v9, v10
	v_ashrrev_i32_e32 v9, 31, v8
	v_lshlrev_b64 v[8:9], 12, v[8:9]
	v_lshl_add_u64 v[8:9], v[6:7], 0, v[8:9]
	v_cvt_pk_bf16_f32 v2, v0, v2
	flat_store_dwordx4 v[8:9], v[2:5] sc1
	ds_read_b32 v0, v85 offset:64
	ds_read_b32 v2, v85 offset:324
	ds_read_b32 v3, v85 offset:584
	ds_read_b32 v4, v85 offset:844
	ds_read_b32 v5, v85 offset:1104
	ds_read_b32 v8, v85 offset:1364
	ds_read_b32 v9, v85 offset:1624
	ds_read_b32 v10, v85 offset:1884
	s_waitcnt lgkmcnt(0)
	v_cvt_pk_bf16_f32 v3, v3, v4
	v_cvt_pk_bf16_f32 v4, v5, v8
	v_or_b32_e32 v8, s92, v87
	v_cvt_pk_bf16_f32 v5, v9, v10
	v_ashrrev_i32_e32 v9, 31, v8
	v_lshlrev_b64 v[8:9], 12, v[8:9]
	v_lshl_add_u64 v[8:9], v[6:7], 0, v[8:9]
	v_cvt_pk_bf16_f32 v2, v0, v2
	flat_store_dwordx4 v[8:9], v[2:5] sc1
	ds_read_b32 v0, v85 offset:96
	ds_read_b32 v2, v85 offset:356
	ds_read_b32 v3, v85 offset:616
	ds_read_b32 v4, v85 offset:876
	ds_read_b32 v5, v85 offset:1136
	ds_read_b32 v8, v85 offset:1396
	ds_read_b32 v9, v85 offset:1656
	ds_read_b32 v10, v85 offset:1916
	s_waitcnt lgkmcnt(0)
	v_cvt_pk_bf16_f32 v3, v3, v4
	v_cvt_pk_bf16_f32 v4, v5, v8
	v_or_b32_e32 v8, s92, v88
	v_cvt_pk_bf16_f32 v5, v9, v10
	v_ashrrev_i32_e32 v9, 31, v8
	v_lshlrev_b64 v[8:9], 12, v[8:9]
	v_lshl_add_u64 v[8:9], v[6:7], 0, v[8:9]
	v_cvt_pk_bf16_f32 v2, v0, v2
	flat_store_dwordx4 v[8:9], v[2:5] sc1
	ds_read_b32 v0, v85 offset:128
	ds_read_b32 v2, v85 offset:388
	ds_read_b32 v3, v85 offset:648
	ds_read_b32 v4, v85 offset:908
	ds_read_b32 v5, v85 offset:1168
	ds_read_b32 v8, v85 offset:1428
	ds_read_b32 v9, v85 offset:1688
	ds_read_b32 v10, v85 offset:1948
	s_waitcnt lgkmcnt(0)
	v_cvt_pk_bf16_f32 v3, v3, v4
	v_cvt_pk_bf16_f32 v4, v5, v8
	v_or_b32_e32 v8, s92, v89
	v_cvt_pk_bf16_f32 v5, v9, v10
	v_ashrrev_i32_e32 v9, 31, v8
	v_lshlrev_b64 v[8:9], 12, v[8:9]
	v_lshl_add_u64 v[8:9], v[6:7], 0, v[8:9]
	v_cvt_pk_bf16_f32 v2, v0, v2
	flat_store_dwordx4 v[8:9], v[2:5] sc1
	ds_read_b32 v0, v85 offset:160
	ds_read_b32 v2, v85 offset:420
	ds_read_b32 v3, v85 offset:680
	ds_read_b32 v4, v85 offset:940
	ds_read_b32 v5, v85 offset:1200
	ds_read_b32 v8, v85 offset:1460
	ds_read_b32 v9, v85 offset:1720
	ds_read_b32 v10, v85 offset:1980
	s_waitcnt lgkmcnt(0)
	v_cvt_pk_bf16_f32 v3, v3, v4
	v_cvt_pk_bf16_f32 v4, v5, v8
	v_or_b32_e32 v8, s92, v90
	v_cvt_pk_bf16_f32 v5, v9, v10
	v_ashrrev_i32_e32 v9, 31, v8
	v_lshlrev_b64 v[8:9], 12, v[8:9]
	v_lshl_add_u64 v[8:9], v[6:7], 0, v[8:9]
	v_cvt_pk_bf16_f32 v2, v0, v2
	flat_store_dwordx4 v[8:9], v[2:5] sc1
	ds_read_b32 v0, v85 offset:192
	ds_read_b32 v2, v85 offset:452
	ds_read_b32 v3, v85 offset:712
	ds_read_b32 v4, v85 offset:972
	ds_read_b32 v5, v85 offset:1232
	ds_read_b32 v8, v85 offset:1492
	ds_read_b32 v9, v85 offset:1752
	ds_read_b32 v10, v85 offset:2012
	s_waitcnt lgkmcnt(0)
	v_cvt_pk_bf16_f32 v3, v3, v4
	v_cvt_pk_bf16_f32 v4, v5, v8
	v_or_b32_e32 v8, s92, v91
	v_cvt_pk_bf16_f32 v5, v9, v10
	v_ashrrev_i32_e32 v9, 31, v8
	v_lshlrev_b64 v[8:9], 12, v[8:9]
	v_lshl_add_u64 v[8:9], v[6:7], 0, v[8:9]
	v_cvt_pk_bf16_f32 v2, v0, v2
	flat_store_dwordx4 v[8:9], v[2:5] sc1
	ds_read_b32 v0, v85 offset:224
	ds_read_b32 v2, v85 offset:484
	ds_read_b32 v3, v85 offset:744
	ds_read_b32 v4, v85 offset:1004
	ds_read_b32 v5, v85 offset:1264
	ds_read_b32 v8, v85 offset:1524
	ds_read_b32 v9, v85 offset:1784
	ds_read_b32 v10, v85 offset:2044
	s_waitcnt lgkmcnt(0)
	v_cvt_pk_bf16_f32 v3, v3, v4
	v_cvt_pk_bf16_f32 v4, v5, v8
	v_or_b32_e32 v8, s92, v92
	v_cvt_pk_bf16_f32 v5, v9, v10
	v_ashrrev_i32_e32 v9, 31, v8
	v_lshlrev_b64 v[8:9], 12, v[8:9]
	v_lshl_add_u64 v[6:7], v[6:7], 0, v[8:9]
	v_cvt_pk_bf16_f32 v2, v0, v2
	flat_store_dwordx4 v[6:7], v[2:5] sc1
	s_waitcnt lgkmcnt(0)

; template <int MAPK>
; __device__ __forceinline__ void transpose_item(const float* W, int K, int N, int ND, bf16_t* WT, const float* g, LAS float* scr, int item, int lane) {
;     ...
;     const int c4 = (lane & 15) * 4, kr = lane >> 4;
;     int src = n0 + c4; if (MAPK == 1) src = inmap(src); if (MAPK == 2) src = upmap(src);
;     f32x4 vv[16];
; #pragma unroll
;     for (int i = 0; i < 16; ++i) { const int kk = 4 * i + kr;
;         vv[i] = (f32x4){0.f, 0.f, 0.f, 0.f};
;         if (src >= 0) vv[i] = *(const f32x4*)(W + (size_t)(k0 + kk) * N + src); }
; #pragma unroll
;     for (int i = 0; i < 16; ++i) { const int kk = 4 * i + kr; f32x4 v = vv[i];
;         if (g) v = v * g[k0 + kk];
;         scr[kk * 65 + c4] = v[0]; scr[kk * 65 + c4 + 1] = v[1]; scr[kk * 65 + c4 + 2] = v[2]; scr[kk * 65 + c4 + 3] = v[3]; }
; __global__ void __launch_bounds__(512, 2) hybrid_fwd(Params p) {
;     ...
;         for (int it = gw; it < 4 * I_LAYER; it += NGW) {
;             const int l = it / I_LAYER; int r = it % I_LAYER; unsigned char* wl = ws + WS_W + (size_t)l * SZ_LAYER;
;             if (r < I_IN) { transpose_item<1>(p.w_in + (size_t)l * D_ * INC, D_, INC, NWIN, (bf16_t*)(WL + OF_WIN), p.norm_mix + l * D_, scr, r, lane); continue; } r -= I_IN;
;             if (r < I_OUT) { transpose_item<0>(p.w_mix_out + (size_t)l * D_ * D_, D_, D_, D_, (bf16_t*)(WL + OF_WOUT), nullptr, scr, r, lane); continue; } r -= I_OUT;
;             if (r < I_Q) { transpose_item<0>(p.wq_x + (size_t)l * D_ * 512, D_, 512, 512, (bf16_t*)(WL + OF_WQ), p.norm_xattn + l * D_, scr, r, lane); continue; } r -= I_Q;
;             if (r < I_KV) { transpose_item<0>(p.wkv_x + (size_t)l * D_ * 1024, D_, 1024, 1024, (bf16_t*)(WL + OF_WKV), p.norm_mem + l * D_, scr, r, lane); continue; } r -= I_KV;
;             if (r < I_O) { transpose_item<0>(p.wo_x + (size_t)l * 512 * D_, 512, D_, D_, (bf16_t*)(WL + OF_WO), nullptr, scr, r, lane); continue; } r -= I_O;
;             if (r < I_UP) { transpose_item<2>(p.w_up + (size_t)l * D_ * 2 * FF_, D_, 2 * FF_, 2 * FF_, (bf16_t*)(WL + OF_WUP), p.norm_ffn + l * D_, scr, r, lane); continue; } r -= I_UP;
;             transpose_item<0>(p.w_down + (size_t)l * FF_ * D_, FF_, D_, D_, (bf16_t*)(WL + OF_WDN), nullptr, scr, r, lane);
.LBB0_23:
	s_mul_hi_i32 s0, s89, 0x288df0cb
	s_lshr_b32 s1, s0, 31
	s_ashr_i32 s0, s0, 11
	s_add_i32 s18, s0, s1
	s_mul_i32 s0, s18, 0xffffcd80
	s_add_i32 s24, s89, s0
	s_ashr_i32 s19, s18, 31
	s_mul_hi_i32 s90, s18, 0x6500000
	s_mul_i32 s91, s18, 0x6500000
	s_cmpk_gt_i32 s24, 0x97f
	s_mov_b64 s[0:1], -1
	s_cbranch_scc0 .LBB0_117
	s_cmpk_gt_u32 s24, 0xd7f
	s_cbranch_scc0 .LBB0_114
	s_cmpk_gt_u32 s24, 0xe7f
	s_cbranch_scc0 .LBB0_87
	s_cmpk_gt_u32 s24, 0x107f
	s_cbranch_scc0 .LBB0_60
	s_cmpk_gt_u32 s24, 0x117f
	s_cbranch_scc0 .LBB0_57
	s_add_u32 s25, s7, s91
	s_addc_u32 s92, s9, s90
	s_cmpk_gt_u32 s24, 0x277f
	s_cbranch_scc0 .LBB0_30
	s_mul_i32 s1, s18, 0x2c00000
	s_mul_hi_i32 s0, s18, 0x2c00000
	s_add_u32 s20, s44, s1
	s_addc_u32 s21, s45, s0
	s_mul_i32 s0, s18, 0xffff9b00
	s_add_i32 s0, s30, s0
	s_add_i32 s0, s0, 0x1b100
	s_and_b32 s1, s0, 0x1ffc0
	s_and_b32 s0, s28, 0x7c0
	v_or_b32_e32 v0, s0, v75
	v_or_b32_e32 v4, s1, v76
	v_lshlrev_b32_e32 v0, 2, v0
	v_lshl_add_u64 v[2:3], s[20:21], 0, v[0:1]
	v_lshlrev_b32_e32 v0, 13, v4
	v_lshl_add_u64 v[62:63], v[2:3], 0, v[0:1]
	v_add_co_u32_e32 v6, vcc, s96, v62
	s_mov_b32 s20, 0x70000
	s_nop 0
	v_addc_co_u32_e32 v7, vcc, 0, v63, vcc
	v_add_co_u32_e32 v10, vcc, s97, v62
	global_load_dwordx4 v[2:5], v[62:63], off
	s_nop 0
	global_load_dwordx4 v[6:9], v[6:7], off
	v_addc_co_u32_e32 v11, vcc, 0, v63, vcc
	v_add_co_u32_e32 v14, vcc, s10, v62
	s_lshl_b32 s1, s1, 1
	s_nop 0
	v_addc_co_u32_e32 v15, vcc, 0, v63, vcc
	v_add_co_u32_e32 v18, vcc, s11, v62
	global_load_dwordx4 v[10:13], v[10:11], off
	s_nop 0
	global_load_dwordx4 v[14:17], v[14:15], off
	v_addc_co_u32_e32 v19, vcc, 0, v63, vcc
	v_add_co_u32_e32 v22, vcc, s85, v62
	v_mov_b32_e32 v79, v1
	s_nop 0
	v_addc_co_u32_e32 v23, vcc, 0, v63, vcc
	v_add_co_u32_e32 v26, vcc, s86, v62
	global_load_dwordx4 v[18:21], v[18:19], off
	s_nop 0
	global_load_dwordx4 v[22:25], v[22:23], off
	v_addc_co_u32_e32 v27, vcc, 0, v63, vcc
	v_add_co_u32_e32 v30, vcc, s87, v62
	s_nop 1
	v_addc_co_u32_e32 v31, vcc, 0, v63, vcc
	v_add_co_u32_e32 v34, vcc, s2, v62
	global_load_dwordx4 v[26:29], v[26:27], off
	s_nop 0
	global_load_dwordx4 v[30:33], v[30:31], off
	v_addc_co_u32_e32 v35, vcc, 0, v63, vcc
	v_add_co_u32_e32 v38, vcc, s3, v62
	s_nop 1
	v_addc_co_u32_e32 v39, vcc, 0, v63, vcc
	v_add_co_u32_e32 v42, vcc, s12, v62
	global_load_dwordx4 v[34:37], v[34:35], off
	s_nop 0
	global_load_dwordx4 v[38:41], v[38:39], off
	v_addc_co_u32_e32 v43, vcc, 0, v63, vcc
	v_add_co_u32_e32 v46, vcc, s13, v62
	s_nop 1
	v_addc_co_u32_e32 v47, vcc, 0, v63, vcc
	v_add_co_u32_e32 v50, vcc, s93, v62
	global_load_dwordx4 v[42:45], v[42:43], off
	s_nop 0
	global_load_dwordx4 v[46:49], v[46:47], off
	v_addc_co_u32_e32 v51, vcc, 0, v63, vcc
	v_add_co_u32_e32 v54, vcc, s94, v62
	s_nop 1
	v_addc_co_u32_e32 v55, vcc, 0, v63, vcc
	global_load_dwordx4 v[50:53], v[50:51], off
	s_nop 0
	global_load_dwordx4 v[54:57], v[54:55], off
	v_add_co_u32_e32 v58, vcc, s20, v62
	s_add_u32 s20, s25, s1
	s_nop 0
	v_addc_co_u32_e32 v59, vcc, 0, v63, vcc
	global_load_dwordx4 v[58:61], v[58:59], off
	v_add_co_u32_e32 v62, vcc, s84, v62
	s_addc_u32 s21, s92, 0
	s_nop 0
	v_addc_co_u32_e32 v63, vcc, 0, v63, vcc
	global_load_dwordx4 v[62:65], v[62:63], off
	s_waitcnt vmcnt(0)
	ds_write2_b32 v83, v2, v3 offset1:1
	ds_write2_b32 v83, v4, v5 offset0:2 offset1:3
	s_waitcnt vmcnt(14)
	ds_write2_b32 v99, v6, v7 offset1:1
	ds_write2_b32 v100, v8, v9 offset1:1
	s_waitcnt vmcnt(13)
	ds_write2_b32 v101, v10, v11 offset1:1
	ds_write2_b32 v102, v12, v13 offset1:1
	s_waitcnt vmcnt(12)
	ds_write2_b32 v103, v14, v15 offset1:1
	ds_write2_b32 v104, v16, v17 offset1:1
	s_waitcnt vmcnt(11)
	ds_write2_b32 v105, v18, v19 offset1:1
	ds_write2_b32 v106, v20, v21 offset1:1
	s_waitcnt vmcnt(10)
	ds_write2_b32 v107, v22, v23 offset1:1
	ds_write2_b32 v108, v24, v25 offset1:1
	s_waitcnt vmcnt(9)
	ds_write2_b32 v109, v26, v27 offset1:1
	ds_write2_b32 v110, v28, v29 offset1:1
	s_waitcnt vmcnt(8)
	ds_write2_b32 v111, v30, v31 offset1:1
	ds_write2_b32 v112, v32, v33 offset1:1
	s_waitcnt vmcnt(7)
	ds_write2_b32 v113, v34, v35 offset1:1
	ds_write2_b32 v114, v36, v37 offset1:1
	s_waitcnt vmcnt(6)
	ds_write2_b32 v115, v38, v39 offset1:1
	ds_write2_b32 v116, v40, v41 offset1:1
	s_waitcnt vmcnt(5)
	ds_write2_b32 v117, v42, v43 offset1:1
	ds_write2_b32 v118, v44, v45 offset1:1
	s_waitcnt vmcnt(4)
	ds_write2_b32 v119, v46, v47 offset1:1
	ds_write2_b32 v120, v48, v49 offset1:1
	s_waitcnt vmcnt(3)
	ds_write2_b32 v121, v50, v51 offset1:1
	ds_write2_b32 v122, v52, v53 offset1:1
	s_waitcnt vmcnt(2)
	ds_write2_b32 v123, v54, v55 offset1:1
	ds_write2_b32 v124, v56, v57 offset1:1
	s_waitcnt vmcnt(1)
	ds_write2_b32 v125, v58, v59 offset1:1
	ds_write2_b32 v126, v60, v61 offset1:1
	s_waitcnt vmcnt(0)
	ds_write2_b32 v127, v62, v63 offset1:1
	ds_write2_b32 v128, v64, v65 offset1:1
	s_waitcnt lgkmcnt(0)
; #define LAS __attribute__((address_space(3)))
; __device__ __forceinline__ unsigned cvt_pk_bf16(float lo, float hi) { unsigned r; asm("v_cvt_pk_bf16_f32 %0, %1, %2" : "=v"(r) : "v"(lo), "v"(hi)); return r; }
; template <int MAPK>
; __device__ __forceinline__ void transpose_item(const float* W, int K, int N, int ND, bf16_t* WT, const float* g, LAS float* scr, int item, int lane) {
;     ...
;     const int c = lane & 7;
; #pragma unroll
;     for (int j = 0; j < 8; ++j) { const int n = (lane >> 3) + 8 * j; const LAS float* sp = scr + (8 * c) * 65 + n;
;         u32x4 o; o.x = cvt_pk_bf16(sp[0], sp[65]); o.y = cvt_pk_bf16(sp[2 * 65], sp[3 * 65]); o.z = cvt_pk_bf16(sp[4 * 65], sp[5 * 65]); o.w = cvt_pk_bf16(sp[6 * 65], sp[7 * 65]);
;         *(u32x4*)(WT + (size_t)(n0 + n) * K + k0 + 8 * c) = o; }
	v_lshl_add_u64 v[2:3], s[20:21], 0, v[78:79]
	ds_read_b32 v0, v85
	ds_read_b32 v4, v85 offset:260
	ds_read_b32 v5, v85 offset:520
	ds_read_b32 v8, v85 offset:780
	ds_read_b32 v9, v85 offset:1040
	ds_read_b32 v10, v85 offset:1300
	ds_read_b32 v11, v85 offset:1560
	ds_read_b32 v12, v85 offset:1820
	s_mov_b64 s[20:21], 0x4f00000
	v_lshl_add_u64 v[6:7], v[2:3], 0, s[20:21]
	s_waitcnt lgkmcnt(6)
	v_cvt_pk_bf16_f32 v2, v0, v4
	v_or_b32_e32 v0, s0, v84
	v_mul_u32_u24_e32 v0, 0x1600, v0
	v_lshlrev_b32_e32 v0, 1, v0
	s_waitcnt lgkmcnt(4)
	v_cvt_pk_bf16_f32 v3, v5, v8
	s_waitcnt lgkmcnt(2)
	v_cvt_pk_bf16_f32 v4, v9, v10
	v_lshl_add_u64 v[8:9], v[6:7], 0, v[0:1]
	s_waitcnt lgkmcnt(0)
	v_cvt_pk_bf16_f32 v5, v11, v12
	flat_store_dwordx4 v[8:9], v[2:5] sc1
	ds_read_b32 v0, v85 offset:32
	ds_read_b32 v2, v85 offset:292
	ds_read_b32 v3, v85 offset:552
	ds_read_b32 v4, v85 offset:812
	ds_read_b32 v5, v85 offset:1072
	ds_read_b32 v8, v85 offset:1332
	ds_read_b32 v9, v85 offset:1592
	ds_read_b32 v10, v85 offset:1852
	s_waitcnt lgkmcnt(0)
	v_cvt_pk_bf16_f32 v2, v0, v2
	v_or_b32_e32 v0, s0, v86
	v_mul_u32_u24_e32 v0, 0x1600, v0
	v_lshlrev_b32_e32 v0, 1, v0
	v_cvt_pk_bf16_f32 v3, v3, v4
	v_cvt_pk_bf16_f32 v4, v5, v8
	v_cvt_pk_bf16_f32 v5, v9, v10
	v_lshl_add_u64 v[8:9], v[6:7], 0, v[0:1]
	flat_store_dwordx4 v[8:9], v[2:5] sc1
	ds_read_b32 v0, v85 offset:64
	ds_read_b32 v2, v85 offset:324
	ds_read_b32 v3, v85 offset:584
	ds_read_b32 v4, v85 offset:844
	ds_read_b32 v5, v85 offset:1104
	ds_read_b32 v8, v85 offset:1364
	ds_read_b32 v9, v85 offset:1624
	ds_read_b32 v10, v85 offset:1884
	s_waitcnt lgkmcnt(0)
	v_cvt_pk_bf16_f32 v2, v0, v2
	v_or_b32_e32 v0, s0, v87
	v_mul_u32_u24_e32 v0, 0x1600, v0
	v_lshlrev_b32_e32 v0, 1, v0
	v_cvt_pk_bf16_f32 v3, v3, v4
	v_cvt_pk_bf16_f32 v4, v5, v8
	v_cvt_pk_bf16_f32 v5, v9, v10
	v_lshl_add_u64 v[8:9], v[6:7], 0, v[0:1]
	flat_store_dwordx4 v[8:9], v[2:5] sc1
	ds_read_b32 v0, v85 offset:96
	ds_read_b32 v2, v85 offset:356
	ds_read_b32 v3, v85 offset:616
	ds_read_b32 v4, v85 offset:876
	ds_read_b32 v5, v85 offset:1136
	ds_read_b32 v8, v85 offset:1396
	ds_read_b32 v9, v85 offset:1656
	ds_read_b32 v10, v85 offset:1916
	s_waitcnt lgkmcnt(0)
	v_cvt_pk_bf16_f32 v2, v0, v2
	v_or_b32_e32 v0, s0, v88
	v_mul_u32_u24_e32 v0, 0x1600, v0
	v_lshlrev_b32_e32 v0, 1, v0
	v_cvt_pk_bf16_f32 v3, v3, v4
	v_cvt_pk_bf16_f32 v4, v5, v8
	v_cvt_pk_bf16_f32 v5, v9, v10
	v_lshl_add_u64 v[8:9], v[6:7], 0, v[0:1]
	flat_store_dwordx4 v[8:9], v[2:5] sc1
	ds_read_b32 v0, v85 offset:128
	ds_read_b32 v2, v85 offset:388
	ds_read_b32 v3, v85 offset:648
	ds_read_b32 v4, v85 offset:908
	ds_read_b32 v5, v85 offset:1168
	ds_read_b32 v8, v85 offset:1428
	ds_read_b32 v9, v85 offset:1688
	ds_read_b32 v10, v85 offset:1948
	s_waitcnt lgkmcnt(0)
	v_cvt_pk_bf16_f32 v2, v0, v2
	v_or_b32_e32 v0, s0, v89
	v_mul_u32_u24_e32 v0, 0x1600, v0
	v_lshlrev_b32_e32 v0, 1, v0
	v_cvt_pk_bf16_f32 v3, v3, v4
	v_cvt_pk_bf16_f32 v4, v5, v8
	v_cvt_pk_bf16_f32 v5, v9, v10
	v_lshl_add_u64 v[8:9], v[6:7], 0, v[0:1]
	flat_store_dwordx4 v[8:9], v[2:5] sc1
	ds_read_b32 v0, v85 offset:160
	ds_read_b32 v2, v85 offset:420
	ds_read_b32 v3, v85 offset:680
	ds_read_b32 v4, v85 offset:940
	ds_read_b32 v5, v85 offset:1200
	ds_read_b32 v8, v85 offset:1460
	ds_read_b32 v9, v85 offset:1720
	ds_read_b32 v10, v85 offset:1980
	s_waitcnt lgkmcnt(0)
	v_cvt_pk_bf16_f32 v2, v0, v2
	v_or_b32_e32 v0, s0, v90
	v_mul_u32_u24_e32 v0, 0x1600, v0
	v_lshlrev_b32_e32 v0, 1, v0
	v_cvt_pk_bf16_f32 v3, v3, v4
	v_cvt_pk_bf16_f32 v4, v5, v8
	v_cvt_pk_bf16_f32 v5, v9, v10
	v_lshl_add_u64 v[8:9], v[6:7], 0, v[0:1]
	flat_store_dwordx4 v[8:9], v[2:5] sc1
	ds_read_b32 v0, v85 offset:192
	ds_read_b32 v2, v85 offset:452
	ds_read_b32 v3, v85 offset:712
	ds_read_b32 v4, v85 offset:972
	ds_read_b32 v5, v85 offset:1232
	ds_read_b32 v8, v85 offset:1492
	ds_read_b32 v9, v85 offset:1752
	ds_read_b32 v10, v85 offset:2012
	s_waitcnt lgkmcnt(0)
	v_cvt_pk_bf16_f32 v2, v0, v2
	v_or_b32_e32 v0, s0, v91
	v_mul_u32_u24_e32 v0, 0x1600, v0
	v_lshlrev_b32_e32 v0, 1, v0
	v_cvt_pk_bf16_f32 v3, v3, v4
	v_cvt_pk_bf16_f32 v4, v5, v8
	v_cvt_pk_bf16_f32 v5, v9, v10
	v_lshl_add_u64 v[8:9], v[6:7], 0, v[0:1]
	flat_store_dwordx4 v[8:9], v[2:5] sc1
	ds_read_b32 v0, v85 offset:224
	ds_read_b32 v2, v85 offset:484
	ds_read_b32 v3, v85 offset:744
	ds_read_b32 v4, v85 offset:1004
	ds_read_b32 v5, v85 offset:1264
	ds_read_b32 v8, v85 offset:1524
	ds_read_b32 v9, v85 offset:1784
	ds_read_b32 v10, v85 offset:2044
	s_waitcnt lgkmcnt(0)
	v_cvt_pk_bf16_f32 v2, v0, v2
	v_or_b32_e32 v0, s0, v92
	v_mul_u32_u24_e32 v0, 0x1600, v0
	v_lshlrev_b32_e32 v0, 1, v0
	v_lshl_add_u64 v[6:7], v[6:7], 0, v[0:1]
	v_cvt_pk_bf16_f32 v3, v3, v4
	v_cvt_pk_bf16_f32 v4, v5, v8
	v_cvt_pk_bf16_f32 v5, v9, v10
	flat_store_dwordx4 v[6:7], v[2:5] sc1
	s_waitcnt lgkmcnt(0)
	s_mov_b64 s[0:1], 0

; #define LAS __attribute__((address_space(3)))
; __device__ __forceinline__ unsigned cvt_pk_bf16(float lo, float hi) { unsigned r; asm("v_cvt_pk_bf16_f32 %0, %1, %2" : "=v"(r) : "v"(lo), "v"(hi)); return r; }
; template <int MAPK>
; __device__ __forceinline__ void transpose_item(const float* W, int K, int N, int ND, bf16_t* WT, const float* g, LAS float* scr, int item, int lane) {
;     ...
;     for (int i = 0; i < 16; ++i) { const int kk = 4 * i + kr; f32x4 v = vv[i];
;         if (g) v = v * g[k0 + kk];
;         scr[kk * 65 + c4] = v[0]; scr[kk * 65 + c4 + 1] = v[1]; scr[kk * 65 + c4 + 2] = v[2]; scr[kk * 65 + c4 + 3] = v[3]; }
;     asm volatile("s_waitcnt lgkmcnt(0)" ::: "memory");
;     const int c = lane & 7;
; #pragma unroll
;     for (int j = 0; j < 8; ++j) { const int n = (lane >> 3) + 8 * j; const LAS float* sp = scr + (8 * c) * 65 + n;
;         u32x4 o; o.x = cvt_pk_bf16(sp[0], sp[65]); o.y = cvt_pk_bf16(sp[2 * 65], sp[3 * 65]); o.z = cvt_pk_bf16(sp[4 * 65], sp[5 * 65]); o.w = cvt_pk_bf16(sp[6 * 65], sp[7 * 65]);
;         *(u32x4*)(WT + (size_t)(n0 + n) * K + k0 + 8 * c) = o; }
;     asm volatile("s_waitcnt lgkmcnt(0)" ::: "memory");
.LBB0_55:
	v_add_u32_e32 v0, 0x1040, v34
	ds_write2_b32 v0, v16, v17 offset1:1
	v_add_u32_e32 v0, 0x1048, v34
	ds_write2_b32 v0, v14, v15 offset1:1
	v_add_u32_e32 v0, 0x1450, v34
	ds_write2_b32 v0, v10, v11 offset1:1
	v_add_u32_e32 v0, 0x1458, v34
	s_and_b32 s0, s94, 0xffc0
	ds_write2_b32 v0, v12, v13 offset1:1
	s_lshl_b32 s1, s93, 1
	s_waitcnt lgkmcnt(0)
	s_add_u32 s20, s25, s1
	s_addc_u32 s21, s92, 0
	v_mov_b32_e32 v79, v1
	ds_read_b32 v0, v85
	ds_read_b32 v4, v85 offset:260
	ds_read_b32 v5, v85 offset:520
	ds_read_b32 v8, v85 offset:780
	ds_read_b32 v9, v85 offset:1040
	ds_read_b32 v10, v85 offset:1300
	ds_read_b32 v11, v85 offset:1560
	ds_read_b32 v12, v85 offset:1820
	v_lshl_add_u64 v[2:3], s[20:21], 0, v[78:79]
	s_mov_b64 s[20:21], 0x2300000
	v_lshl_add_u64 v[6:7], v[2:3], 0, s[20:21]
	s_waitcnt lgkmcnt(0)
	v_cvt_pk_bf16_f32 v2, v0, v4
	v_or_b32_e32 v0, s0, v84
	v_lshlrev_b32_e32 v0, 12, v0
	v_cvt_pk_bf16_f32 v3, v5, v8
	v_cvt_pk_bf16_f32 v4, v9, v10
	v_lshl_add_u64 v[8:9], v[6:7], 0, v[0:1]
	v_cvt_pk_bf16_f32 v5, v11, v12
	flat_store_dwordx4 v[8:9], v[2:5] sc1
	ds_read_b32 v0, v85 offset:32
	ds_read_b32 v2, v85 offset:292
	ds_read_b32 v3, v85 offset:552
	ds_read_b32 v4, v85 offset:812
	ds_read_b32 v5, v85 offset:1072
	ds_read_b32 v8, v85 offset:1332
	ds_read_b32 v9, v85 offset:1592
	ds_read_b32 v10, v85 offset:1852
	s_waitcnt lgkmcnt(0)
	v_cvt_pk_bf16_f32 v2, v0, v2
	v_or_b32_e32 v0, s0, v86
	v_lshlrev_b32_e32 v0, 12, v0
	v_cvt_pk_bf16_f32 v3, v3, v4
	v_cvt_pk_bf16_f32 v4, v5, v8
	v_cvt_pk_bf16_f32 v5, v9, v10
	v_lshl_add_u64 v[8:9], v[6:7], 0, v[0:1]
	flat_store_dwordx4 v[8:9], v[2:5] sc1
	ds_read_b32 v0, v85 offset:64
	ds_read_b32 v2, v85 offset:324
	ds_read_b32 v3, v85 offset:584
	ds_read_b32 v4, v85 offset:844
	ds_read_b32 v5, v85 offset:1104
	ds_read_b32 v8, v85 offset:1364
	ds_read_b32 v9, v85 offset:1624
	ds_read_b32 v10, v85 offset:1884
	s_waitcnt lgkmcnt(0)
	v_cvt_pk_bf16_f32 v2, v0, v2
	v_or_b32_e32 v0, s0, v87
	v_lshlrev_b32_e32 v0, 12, v0
	v_cvt_pk_bf16_f32 v3, v3, v4
	v_cvt_pk_bf16_f32 v4, v5, v8
	v_cvt_pk_bf16_f32 v5, v9, v10
	v_lshl_add_u64 v[8:9], v[6:7], 0, v[0:1]
	flat_store_dwordx4 v[8:9], v[2:5] sc1
	ds_read_b32 v0, v85 offset:96
	ds_read_b32 v2, v85 offset:356
	ds_read_b32 v3, v85 offset:616
	ds_read_b32 v4, v85 offset:876
	ds_read_b32 v5, v85 offset:1136
	ds_read_b32 v8, v85 offset:1396
	ds_read_b32 v9, v85 offset:1656
	ds_read_b32 v10, v85 offset:1916
	s_waitcnt lgkmcnt(0)
	v_cvt_pk_bf16_f32 v2, v0, v2
	v_or_b32_e32 v0, s0, v88
	v_lshlrev_b32_e32 v0, 12, v0
	v_cvt_pk_bf16_f32 v3, v3, v4
	v_cvt_pk_bf16_f32 v4, v5, v8
	v_cvt_pk_bf16_f32 v5, v9, v10
	v_lshl_add_u64 v[8:9], v[6:7], 0, v[0:1]
	flat_store_dwordx4 v[8:9], v[2:5] sc1
	ds_read_b32 v0, v85 offset:128
	ds_read_b32 v2, v85 offset:388
	ds_read_b32 v3, v85 offset:648
	ds_read_b32 v4, v85 offset:908
	ds_read_b32 v5, v85 offset:1168
	ds_read_b32 v8, v85 offset:1428
	ds_read_b32 v9, v85 offset:1688
	ds_read_b32 v10, v85 offset:1948
	s_waitcnt lgkmcnt(0)
	v_cvt_pk_bf16_f32 v2, v0, v2
	v_or_b32_e32 v0, s0, v89
	v_lshlrev_b32_e32 v0, 12, v0
	v_cvt_pk_bf16_f32 v3, v3, v4
	v_cvt_pk_bf16_f32 v4, v5, v8
	v_cvt_pk_bf16_f32 v5, v9, v10
	v_lshl_add_u64 v[8:9], v[6:7], 0, v[0:1]
	flat_store_dwordx4 v[8:9], v[2:5] sc1
	ds_read_b32 v0, v85 offset:160
	ds_read_b32 v2, v85 offset:420
	ds_read_b32 v3, v85 offset:680
	ds_read_b32 v4, v85 offset:940
	ds_read_b32 v5, v85 offset:1200
	ds_read_b32 v8, v85 offset:1460
	ds_read_b32 v9, v85 offset:1720
	ds_read_b32 v10, v85 offset:1980
	s_waitcnt lgkmcnt(0)
	v_cvt_pk_bf16_f32 v2, v0, v2
	v_or_b32_e32 v0, s0, v90
	v_lshlrev_b32_e32 v0, 12, v0
	v_cvt_pk_bf16_f32 v3, v3, v4
	v_cvt_pk_bf16_f32 v4, v5, v8
	v_cvt_pk_bf16_f32 v5, v9, v10
	v_lshl_add_u64 v[8:9], v[6:7], 0, v[0:1]
	flat_store_dwordx4 v[8:9], v[2:5] sc1
	ds_read_b32 v0, v85 offset:192
	ds_read_b32 v2, v85 offset:452
	ds_read_b32 v3, v85 offset:712
	ds_read_b32 v4, v85 offset:972
	ds_read_b32 v5, v85 offset:1232
	ds_read_b32 v8, v85 offset:1492
	ds_read_b32 v9, v85 offset:1752
	ds_read_b32 v10, v85 offset:2012
	s_waitcnt lgkmcnt(0)
	v_cvt_pk_bf16_f32 v2, v0, v2
	v_or_b32_e32 v0, s0, v91
	v_lshlrev_b32_e32 v0, 12, v0
	v_cvt_pk_bf16_f32 v3, v3, v4
	v_cvt_pk_bf16_f32 v4, v5, v8
	v_cvt_pk_bf16_f32 v5, v9, v10
	v_lshl_add_u64 v[8:9], v[6:7], 0, v[0:1]
	flat_store_dwordx4 v[8:9], v[2:5] sc1
	ds_read_b32 v0, v85 offset:224
	ds_read_b32 v2, v85 offset:484
	ds_read_b32 v3, v85 offset:744
	ds_read_b32 v4, v85 offset:1004
	ds_read_b32 v5, v85 offset:1264
	ds_read_b32 v8, v85 offset:1524
	ds_read_b32 v9, v85 offset:1784
	ds_read_b32 v10, v85 offset:2044
	s_waitcnt lgkmcnt(0)
	v_cvt_pk_bf16_f32 v2, v0, v2
	v_or_b32_e32 v0, s0, v92
	v_lshlrev_b32_e32 v0, 12, v0
	v_lshl_add_u64 v[6:7], v[6:7], 0, v[0:1]
	v_cvt_pk_bf16_f32 v3, v3, v4
	v_cvt_pk_bf16_f32 v4, v5, v8
	v_cvt_pk_bf16_f32 v5, v9, v10
	flat_store_dwordx4 v[6:7], v[2:5] sc1
	s_waitcnt lgkmcnt(0)
	s_mov_b32 s93, 0x60000
	s_mov_b32 s94, 0x68000

; template <int MAPK>
; __device__ __forceinline__ void transpose_item(const float* W, int K, int N, int ND, bf16_t* WT, const float* g, LAS float* scr, int item, int lane) {
;     ...
;     const int c4 = (lane & 15) * 4, kr = lane >> 4;
;     int src = n0 + c4; if (MAPK == 1) src = inmap(src); if (MAPK == 2) src = upmap(src);
;     f32x4 vv[16];
; #pragma unroll
;     for (int i = 0; i < 16; ++i) { const int kk = 4 * i + kr;
;         vv[i] = (f32x4){0.f, 0.f, 0.f, 0.f};
;         if (src >= 0) vv[i] = *(const f32x4*)(W + (size_t)(k0 + kk) * N + src); }
; #pragma unroll
;     for (int i = 0; i < 16; ++i) { const int kk = 4 * i + kr; f32x4 v = vv[i];
;         if (g) v = v * g[k0 + kk];
;         scr[kk * 65 + c4] = v[0]; scr[kk * 65 + c4 + 1] = v[1]; scr[kk * 65 + c4 + 2] = v[2]; scr[kk * 65 + c4 + 3] = v[3]; }
; __global__ void __launch_bounds__(512, 2) hybrid_fwd(Params p) {
;     ...
;             if (r < I_O) { transpose_item<0>(p.wo_x + (size_t)l * 512 * D_, 512, D_, D_, (bf16_t*)(WL + OF_WO), nullptr, scr, r, lane); continue; } r -= I_O;
.LBB0_57:
	s_andn2_b64 vcc, exec, s[0:1]
	s_cbranch_vccnz .LBB0_59
	v_readlane_b32 s68, v255, 4
	s_lshl_b64 s[0:1], s[18:19], 22
	v_readlane_b32 s82, v255, 18
	v_readlane_b32 s83, v255, 19
	s_add_u32 s20, s82, s0
	s_addc_u32 s21, s83, s1
	s_add_u32 s1, s7, s91
	s_addc_u32 s22, s9, s90
	s_lshl_b32 s0, s18, 8
	s_sub_i32 s0, s30, s0
	s_and_b32 s23, s0, 0x1c0
	s_and_b32 s0, s28, 0x7c0
	v_or_b32_e32 v0, s0, v75
	v_bitop3_b32 v4, s23, v76, v129 bitop3:0xde
	v_lshlrev_b32_e32 v0, 2, v0
	v_lshl_add_u64 v[2:3], s[20:21], 0, v[0:1]
	v_lshlrev_b32_e32 v0, 13, v4
	v_lshl_add_u64 v[62:63], v[2:3], 0, v[0:1]
	v_add_co_u32_e32 v6, vcc, s96, v62
	s_mov_b32 s20, 0x70000
	s_nop 0
	v_addc_co_u32_e32 v7, vcc, 0, v63, vcc
	v_add_co_u32_e32 v10, vcc, s97, v62
	global_load_dwordx4 v[2:5], v[62:63], off
	s_nop 0
	global_load_dwordx4 v[6:9], v[6:7], off
	v_addc_co_u32_e32 v11, vcc, 0, v63, vcc
	v_add_co_u32_e32 v14, vcc, s10, v62
	v_mov_b32_e32 v79, v1
	s_nop 0
	v_addc_co_u32_e32 v15, vcc, 0, v63, vcc
	v_add_co_u32_e32 v18, vcc, s11, v62
	global_load_dwordx4 v[10:13], v[10:11], off
	s_nop 0
	global_load_dwordx4 v[14:17], v[14:15], off
	v_addc_co_u32_e32 v19, vcc, 0, v63, vcc
	v_add_co_u32_e32 v22, vcc, s85, v62
	v_readlane_b32 s69, v255, 5
	s_nop 0
	v_addc_co_u32_e32 v23, vcc, 0, v63, vcc
	v_add_co_u32_e32 v26, vcc, s86, v62
	global_load_dwordx4 v[18:21], v[18:19], off
	s_nop 0
	global_load_dwordx4 v[22:25], v[22:23], off
	v_addc_co_u32_e32 v27, vcc, 0, v63, vcc
	v_add_co_u32_e32 v30, vcc, s87, v62
	v_readlane_b32 s70, v255, 6
	s_nop 0
	v_addc_co_u32_e32 v31, vcc, 0, v63, vcc
	v_add_co_u32_e32 v34, vcc, s2, v62
	global_load_dwordx4 v[26:29], v[26:27], off
	s_nop 0
	global_load_dwordx4 v[30:33], v[30:31], off
	v_addc_co_u32_e32 v35, vcc, 0, v63, vcc
	v_add_co_u32_e32 v38, vcc, s3, v62
	v_readlane_b32 s71, v255, 7
	s_nop 0
	v_addc_co_u32_e32 v39, vcc, 0, v63, vcc
	v_add_co_u32_e32 v42, vcc, s12, v62
	global_load_dwordx4 v[34:37], v[34:35], off
	s_nop 0
	global_load_dwordx4 v[38:41], v[38:39], off
	v_addc_co_u32_e32 v43, vcc, 0, v63, vcc
	v_add_co_u32_e32 v46, vcc, s13, v62
	v_readlane_b32 s72, v255, 8
	s_nop 0
	v_addc_co_u32_e32 v47, vcc, 0, v63, vcc
	v_add_co_u32_e32 v50, vcc, s93, v62
	global_load_dwordx4 v[42:45], v[42:43], off
	s_nop 0
	global_load_dwordx4 v[46:49], v[46:47], off
	v_addc_co_u32_e32 v51, vcc, 0, v63, vcc
	v_add_co_u32_e32 v54, vcc, s94, v62
	v_readlane_b32 s73, v255, 9
	s_nop 0
	v_addc_co_u32_e32 v55, vcc, 0, v63, vcc
	global_load_dwordx4 v[50:53], v[50:51], off
	s_nop 0
	global_load_dwordx4 v[54:57], v[54:55], off
	v_add_co_u32_e32 v58, vcc, s20, v62
	s_xor_b32 s20, s23, 0x100
	s_nop 0
	v_addc_co_u32_e32 v59, vcc, 0, v63, vcc
	global_load_dwordx4 v[58:61], v[58:59], off
	v_add_co_u32_e32 v62, vcc, s84, v62
	s_lshl_b32 s20, s20, 1
	s_nop 0
	v_addc_co_u32_e32 v63, vcc, 0, v63, vcc
	global_load_dwordx4 v[62:65], v[62:63], off
	s_add_u32 s20, s1, s20
	s_addc_u32 s21, s22, 0
	v_readlane_b32 s74, v255, 10
	v_readlane_b32 s75, v255, 11
	v_readlane_b32 s76, v255, 12
	v_readlane_b32 s77, v255, 13
	v_readlane_b32 s78, v255, 14
	v_readlane_b32 s79, v255, 15
	v_readlane_b32 s80, v255, 16
	v_readlane_b32 s81, v255, 17
	s_waitcnt vmcnt(0)
	ds_write2_b32 v83, v2, v3 offset1:1
	ds_write2_b32 v83, v4, v5 offset0:2 offset1:3
	ds_write2_b32 v99, v6, v7 offset1:1
	ds_write2_b32 v100, v8, v9 offset1:1
	ds_write2_b32 v101, v10, v11 offset1:1
	ds_write2_b32 v102, v12, v13 offset1:1
	ds_write2_b32 v103, v14, v15 offset1:1
	ds_write2_b32 v104, v16, v17 offset1:1
	ds_write2_b32 v105, v18, v19 offset1:1
	ds_write2_b32 v106, v20, v21 offset1:1
	ds_write2_b32 v107, v22, v23 offset1:1
	ds_write2_b32 v108, v24, v25 offset1:1
	ds_write2_b32 v109, v26, v27 offset1:1
	ds_write2_b32 v110, v28, v29 offset1:1
	ds_write2_b32 v111, v30, v31 offset1:1
	ds_write2_b32 v112, v32, v33 offset1:1
	ds_write2_b32 v113, v34, v35 offset1:1
	ds_write2_b32 v114, v36, v37 offset1:1
	ds_write2_b32 v115, v38, v39 offset1:1
	ds_write2_b32 v116, v40, v41 offset1:1
	ds_write2_b32 v117, v42, v43 offset1:1
	ds_write2_b32 v118, v44, v45 offset1:1
	ds_write2_b32 v119, v46, v47 offset1:1
	ds_write2_b32 v120, v48, v49 offset1:1
	ds_write2_b32 v121, v50, v51 offset1:1
	ds_write2_b32 v122, v52, v53 offset1:1
	ds_write2_b32 v123, v54, v55 offset1:1
	ds_write2_b32 v124, v56, v57 offset1:1
	ds_write2_b32 v125, v58, v59 offset1:1
	ds_write2_b32 v126, v60, v61 offset1:1
	ds_write2_b32 v127, v62, v63 offset1:1
	ds_write2_b32 v128, v64, v65 offset1:1
	s_waitcnt lgkmcnt(0)
; #define LAS __attribute__((address_space(3)))
; __device__ __forceinline__ unsigned cvt_pk_bf16(float lo, float hi) { unsigned r; asm("v_cvt_pk_bf16_f32 %0, %1, %2" : "=v"(r) : "v"(lo), "v"(hi)); return r; }
; template <int MAPK>
; __device__ __forceinline__ void transpose_item(const float* W, int K, int N, int ND, bf16_t* WT, const float* g, LAS float* scr, int item, int lane) {
;     ...
;     const int c = lane & 7;
; #pragma unroll
;     for (int j = 0; j < 8; ++j) { const int n = (lane >> 3) + 8 * j; const LAS float* sp = scr + (8 * c) * 65 + n;
;         u32x4 o; o.x = cvt_pk_bf16(sp[0], sp[65]); o.y = cvt_pk_bf16(sp[2 * 65], sp[3 * 65]); o.z = cvt_pk_bf16(sp[4 * 65], sp[5 * 65]); o.w = cvt_pk_bf16(sp[6 * 65], sp[7 * 65]);
;         *(u32x4*)(WT + (size_t)(n0 + n) * K + k0 + 8 * c) = o; }
	ds_read_b32 v0, v85
	ds_read_b32 v4, v85 offset:260
	ds_read_b32 v5, v85 offset:520
	ds_read_b32 v8, v85 offset:780
	ds_read_b32 v9, v85 offset:1040
	ds_read_b32 v10, v85 offset:1300
	ds_read_b32 v11, v85 offset:1560
	ds_read_b32 v12, v85 offset:1820
	v_lshl_add_u64 v[2:3], s[20:21], 0, v[78:79]
	s_mov_b64 s[20:21], 0x2100000
	v_lshl_add_u64 v[6:7], v[2:3], 0, s[20:21]
	s_waitcnt lgkmcnt(0)
	v_cvt_pk_bf16_f32 v2, v0, v4
	v_or_b32_e32 v0, s0, v84
	v_lshlrev_b32_e32 v0, 10, v0
	v_cvt_pk_bf16_f32 v3, v5, v8
	v_cvt_pk_bf16_f32 v4, v9, v10
	v_lshl_add_u64 v[8:9], v[6:7], 0, v[0:1]
	v_cvt_pk_bf16_f32 v5, v11, v12
	flat_store_dwordx4 v[8:9], v[2:5] sc1
	ds_read_b32 v0, v85 offset:32
	ds_read_b32 v2, v85 offset:292
	ds_read_b32 v3, v85 offset:552
	ds_read_b32 v4, v85 offset:812
	ds_read_b32 v5, v85 offset:1072
	ds_read_b32 v8, v85 offset:1332
	ds_read_b32 v9, v85 offset:1592
	ds_read_b32 v10, v85 offset:1852
	s_waitcnt lgkmcnt(0)
	v_cvt_pk_bf16_f32 v2, v0, v2
	v_or_b32_e32 v0, s0, v86
	v_lshlrev_b32_e32 v0, 10, v0
	v_cvt_pk_bf16_f32 v3, v3, v4
	v_cvt_pk_bf16_f32 v4, v5, v8
	v_cvt_pk_bf16_f32 v5, v9, v10
	v_lshl_add_u64 v[8:9], v[6:7], 0, v[0:1]
	flat_store_dwordx4 v[8:9], v[2:5] sc1
	ds_read_b32 v0, v85 offset:64
	ds_read_b32 v2, v85 offset:324
	ds_read_b32 v3, v85 offset:584
	ds_read_b32 v4, v85 offset:844
	ds_read_b32 v5, v85 offset:1104
	ds_read_b32 v8, v85 offset:1364
	ds_read_b32 v9, v85 offset:1624
	ds_read_b32 v10, v85 offset:1884
	s_waitcnt lgkmcnt(0)
	v_cvt_pk_bf16_f32 v2, v0, v2
	v_or_b32_e32 v0, s0, v87
	v_lshlrev_b32_e32 v0, 10, v0
	v_cvt_pk_bf16_f32 v3, v3, v4
	v_cvt_pk_bf16_f32 v4, v5, v8
	v_cvt_pk_bf16_f32 v5, v9, v10
	v_lshl_add_u64 v[8:9], v[6:7], 0, v[0:1]
	flat_store_dwordx4 v[8:9], v[2:5] sc1
	ds_read_b32 v0, v85 offset:96
	ds_read_b32 v2, v85 offset:356
	ds_read_b32 v3, v85 offset:616
	ds_read_b32 v4, v85 offset:876
	ds_read_b32 v5, v85 offset:1136
	ds_read_b32 v8, v85 offset:1396
	ds_read_b32 v9, v85 offset:1656
	ds_read_b32 v10, v85 offset:1916
	s_waitcnt lgkmcnt(0)
	v_cvt_pk_bf16_f32 v2, v0, v2
	v_or_b32_e32 v0, s0, v88
	v_lshlrev_b32_e32 v0, 10, v0
	v_cvt_pk_bf16_f32 v3, v3, v4
	v_cvt_pk_bf16_f32 v4, v5, v8
	v_cvt_pk_bf16_f32 v5, v9, v10
	v_lshl_add_u64 v[8:9], v[6:7], 0, v[0:1]
	flat_store_dwordx4 v[8:9], v[2:5] sc1
	ds_read_b32 v0, v85 offset:128
	ds_read_b32 v2, v85 offset:388
	ds_read_b32 v3, v85 offset:648
	ds_read_b32 v4, v85 offset:908
	ds_read_b32 v5, v85 offset:1168
	ds_read_b32 v8, v85 offset:1428
	ds_read_b32 v9, v85 offset:1688
	ds_read_b32 v10, v85 offset:1948
	s_waitcnt lgkmcnt(0)
	v_cvt_pk_bf16_f32 v2, v0, v2
	v_or_b32_e32 v0, s0, v89
	v_lshlrev_b32_e32 v0, 10, v0
	v_cvt_pk_bf16_f32 v3, v3, v4
	v_cvt_pk_bf16_f32 v4, v5, v8
	v_cvt_pk_bf16_f32 v5, v9, v10
	v_lshl_add_u64 v[8:9], v[6:7], 0, v[0:1]
	flat_store_dwordx4 v[8:9], v[2:5] sc1
	ds_read_b32 v0, v85 offset:160
	ds_read_b32 v2, v85 offset:420
	ds_read_b32 v3, v85 offset:680
	ds_read_b32 v4, v85 offset:940
	ds_read_b32 v5, v85 offset:1200
	ds_read_b32 v8, v85 offset:1460
	ds_read_b32 v9, v85 offset:1720
	ds_read_b32 v10, v85 offset:1980
	s_waitcnt lgkmcnt(0)
	v_cvt_pk_bf16_f32 v2, v0, v2
	v_or_b32_e32 v0, s0, v90
	v_lshlrev_b32_e32 v0, 10, v0
	v_cvt_pk_bf16_f32 v3, v3, v4
	v_cvt_pk_bf16_f32 v4, v5, v8
	v_cvt_pk_bf16_f32 v5, v9, v10
	v_lshl_add_u64 v[8:9], v[6:7], 0, v[0:1]
	flat_store_dwordx4 v[8:9], v[2:5] sc1
	ds_read_b32 v0, v85 offset:192
	ds_read_b32 v2, v85 offset:452
	ds_read_b32 v3, v85 offset:712
	ds_read_b32 v4, v85 offset:972
	ds_read_b32 v5, v85 offset:1232
	ds_read_b32 v8, v85 offset:1492
	ds_read_b32 v9, v85 offset:1752
	ds_read_b32 v10, v85 offset:2012
	s_waitcnt lgkmcnt(0)
	v_cvt_pk_bf16_f32 v2, v0, v2
	v_or_b32_e32 v0, s0, v91
	v_lshlrev_b32_e32 v0, 10, v0
	v_cvt_pk_bf16_f32 v3, v3, v4
	v_cvt_pk_bf16_f32 v4, v5, v8
	v_cvt_pk_bf16_f32 v5, v9, v10
	v_lshl_add_u64 v[8:9], v[6:7], 0, v[0:1]
	flat_store_dwordx4 v[8:9], v[2:5] sc1
	ds_read_b32 v0, v85 offset:224
	ds_read_b32 v2, v85 offset:484
	ds_read_b32 v3, v85 offset:744
	ds_read_b32 v4, v85 offset:1004
	ds_read_b32 v5, v85 offset:1264
	ds_read_b32 v8, v85 offset:1524
	ds_read_b32 v9, v85 offset:1784
	ds_read_b32 v10, v85 offset:2044
	s_waitcnt lgkmcnt(0)
	v_cvt_pk_bf16_f32 v2, v0, v2
	v_or_b32_e32 v0, s0, v92
	v_lshlrev_b32_e32 v0, 10, v0
	v_lshl_add_u64 v[6:7], v[6:7], 0, v[0:1]
	v_cvt_pk_bf16_f32 v3, v3, v4
	v_cvt_pk_bf16_f32 v4, v5, v8
	v_cvt_pk_bf16_f32 v5, v9, v10
	flat_store_dwordx4 v[6:7], v[2:5] sc1
	s_waitcnt lgkmcnt(0)

; #define LAS __attribute__((address_space(3)))
; __device__ __forceinline__ unsigned cvt_pk_bf16(float lo, float hi) { unsigned r; asm("v_cvt_pk_bf16_f32 %0, %1, %2" : "=v"(r) : "v"(lo), "v"(hi)); return r; }
; template <int MAPK>
; __device__ __forceinline__ void transpose_item(const float* W, int K, int N, int ND, bf16_t* WT, const float* g, LAS float* scr, int item, int lane) {
;     ...
;     for (int i = 0; i < 16; ++i) { const int kk = 4 * i + kr; f32x4 v = vv[i];
;         if (g) v = v * g[k0 + kk];
;         scr[kk * 65 + c4] = v[0]; scr[kk * 65 + c4 + 1] = v[1]; scr[kk * 65 + c4 + 2] = v[2]; scr[kk * 65 + c4 + 3] = v[3]; }
;     asm volatile("s_waitcnt lgkmcnt(0)" ::: "memory");
;     const int c = lane & 7;
; #pragma unroll
;     for (int j = 0; j < 8; ++j) { const int n = (lane >> 3) + 8 * j; const LAS float* sp = scr + (8 * c) * 65 + n;
;         u32x4 o; o.x = cvt_pk_bf16(sp[0], sp[65]); o.y = cvt_pk_bf16(sp[2 * 65], sp[3 * 65]); o.z = cvt_pk_bf16(sp[4 * 65], sp[5 * 65]); o.w = cvt_pk_bf16(sp[6 * 65], sp[7 * 65]);
;         *(u32x4*)(WT + (size_t)(n0 + n) * K + k0 + 8 * c) = o; }
;     asm volatile("s_waitcnt lgkmcnt(0)" ::: "memory");
.LBB0_85:
	v_add_u32_e32 v0, 0x1040, v34
	ds_write2_b32 v0, v16, v17 offset1:1
	v_add_u32_e32 v0, 0x1048, v34
	ds_write2_b32 v0, v14, v15 offset1:1
	v_add_u32_e32 v0, 0x1450, v34
	s_add_u32 s0, s7, s91
	ds_write2_b32 v0, v10, v11 offset1:1
	v_add_u32_e32 v0, 0x1458, v34
	s_addc_u32 s1, s9, s90
	ds_write2_b32 v0, v12, v13 offset1:1
	s_lshl_b32 s20, s92, 1
	s_waitcnt lgkmcnt(0)
	s_add_u32 s0, s0, s20
	s_addc_u32 s1, s1, 0
	v_mov_b32_e32 v79, v1
	ds_read_b32 v0, v85
	ds_read_b32 v4, v85 offset:260
	ds_read_b32 v5, v85 offset:520
	ds_read_b32 v8, v85 offset:780
	ds_read_b32 v9, v85 offset:1040
	ds_read_b32 v10, v85 offset:1300
	ds_read_b32 v11, v85 offset:1560
	ds_read_b32 v12, v85 offset:1820
	v_lshl_add_u64 v[2:3], s[0:1], 0, v[78:79]
	s_mov_b64 s[0:1], 0x1d00000
	v_lshl_add_u64 v[6:7], v[2:3], 0, s[0:1]
	s_waitcnt lgkmcnt(0)
	v_cvt_pk_bf16_f32 v2, v0, v4
	v_or_b32_e32 v0, s25, v84
	v_lshlrev_b32_e32 v0, 12, v0
	v_cvt_pk_bf16_f32 v3, v5, v8
	v_cvt_pk_bf16_f32 v4, v9, v10
	v_lshl_add_u64 v[8:9], v[6:7], 0, v[0:1]
	v_cvt_pk_bf16_f32 v5, v11, v12
	flat_store_dwordx4 v[8:9], v[2:5] sc1
	ds_read_b32 v0, v85 offset:32
	ds_read_b32 v2, v85 offset:292
	ds_read_b32 v3, v85 offset:552
	ds_read_b32 v4, v85 offset:812
	ds_read_b32 v5, v85 offset:1072
	ds_read_b32 v8, v85 offset:1332
	ds_read_b32 v9, v85 offset:1592
	ds_read_b32 v10, v85 offset:1852
	s_waitcnt lgkmcnt(0)
	v_cvt_pk_bf16_f32 v2, v0, v2
	v_or_b32_e32 v0, s25, v86
	v_lshlrev_b32_e32 v0, 12, v0
	v_cvt_pk_bf16_f32 v3, v3, v4
	v_cvt_pk_bf16_f32 v4, v5, v8
	v_cvt_pk_bf16_f32 v5, v9, v10
	v_lshl_add_u64 v[8:9], v[6:7], 0, v[0:1]
	flat_store_dwordx4 v[8:9], v[2:5] sc1
	ds_read_b32 v0, v85 offset:64
	ds_read_b32 v2, v85 offset:324
	ds_read_b32 v3, v85 offset:584
	ds_read_b32 v4, v85 offset:844
	ds_read_b32 v5, v85 offset:1104
	ds_read_b32 v8, v85 offset:1364
	ds_read_b32 v9, v85 offset:1624
	ds_read_b32 v10, v85 offset:1884
	s_waitcnt lgkmcnt(0)
	v_cvt_pk_bf16_f32 v2, v0, v2
	v_or_b32_e32 v0, s25, v87
	v_lshlrev_b32_e32 v0, 12, v0
	v_cvt_pk_bf16_f32 v3, v3, v4
	v_cvt_pk_bf16_f32 v4, v5, v8
	v_cvt_pk_bf16_f32 v5, v9, v10
	v_lshl_add_u64 v[8:9], v[6:7], 0, v[0:1]
	flat_store_dwordx4 v[8:9], v[2:5] sc1
	ds_read_b32 v0, v85 offset:96
	ds_read_b32 v2, v85 offset:356
	ds_read_b32 v3, v85 offset:616
	ds_read_b32 v4, v85 offset:876
	ds_read_b32 v5, v85 offset:1136
	ds_read_b32 v8, v85 offset:1396
	ds_read_b32 v9, v85 offset:1656
	ds_read_b32 v10, v85 offset:1916
	s_waitcnt lgkmcnt(0)
	v_cvt_pk_bf16_f32 v2, v0, v2
	v_or_b32_e32 v0, s25, v88
	v_lshlrev_b32_e32 v0, 12, v0
	v_cvt_pk_bf16_f32 v3, v3, v4
	v_cvt_pk_bf16_f32 v4, v5, v8
	v_cvt_pk_bf16_f32 v5, v9, v10
	v_lshl_add_u64 v[8:9], v[6:7], 0, v[0:1]
	flat_store_dwordx4 v[8:9], v[2:5] sc1
	ds_read_b32 v0, v85 offset:128
	ds_read_b32 v2, v85 offset:388
	ds_read_b32 v3, v85 offset:648
	ds_read_b32 v4, v85 offset:908
	ds_read_b32 v5, v85 offset:1168
	ds_read_b32 v8, v85 offset:1428
	ds_read_b32 v9, v85 offset:1688
	ds_read_b32 v10, v85 offset:1948
	s_waitcnt lgkmcnt(0)
	v_cvt_pk_bf16_f32 v2, v0, v2
	v_or_b32_e32 v0, s25, v89
	v_lshlrev_b32_e32 v0, 12, v0
	v_cvt_pk_bf16_f32 v3, v3, v4
	v_cvt_pk_bf16_f32 v4, v5, v8
	v_cvt_pk_bf16_f32 v5, v9, v10
	v_lshl_add_u64 v[8:9], v[6:7], 0, v[0:1]
	flat_store_dwordx4 v[8:9], v[2:5] sc1
	ds_read_b32 v0, v85 offset:160
	ds_read_b32 v2, v85 offset:420
	ds_read_b32 v3, v85 offset:680
	ds_read_b32 v4, v85 offset:940
	ds_read_b32 v5, v85 offset:1200
	ds_read_b32 v8, v85 offset:1460
	ds_read_b32 v9, v85 offset:1720
	ds_read_b32 v10, v85 offset:1980
	s_waitcnt lgkmcnt(0)
	v_cvt_pk_bf16_f32 v2, v0, v2
	v_or_b32_e32 v0, s25, v90
	v_lshlrev_b32_e32 v0, 12, v0
	v_cvt_pk_bf16_f32 v3, v3, v4
	v_cvt_pk_bf16_f32 v4, v5, v8
	v_cvt_pk_bf16_f32 v5, v9, v10
	v_lshl_add_u64 v[8:9], v[6:7], 0, v[0:1]
	flat_store_dwordx4 v[8:9], v[2:5] sc1
	ds_read_b32 v0, v85 offset:192
	ds_read_b32 v2, v85 offset:452
	ds_read_b32 v3, v85 offset:712
	ds_read_b32 v4, v85 offset:972
	ds_read_b32 v5, v85 offset:1232
	ds_read_b32 v8, v85 offset:1492
	ds_read_b32 v9, v85 offset:1752
	ds_read_b32 v10, v85 offset:2012
	s_waitcnt lgkmcnt(0)
	v_cvt_pk_bf16_f32 v2, v0, v2
	v_or_b32_e32 v0, s25, v91
	v_lshlrev_b32_e32 v0, 12, v0
	v_cvt_pk_bf16_f32 v3, v3, v4
	v_cvt_pk_bf16_f32 v4, v5, v8
	v_cvt_pk_bf16_f32 v5, v9, v10
	v_lshl_add_u64 v[8:9], v[6:7], 0, v[0:1]
	flat_store_dwordx4 v[8:9], v[2:5] sc1
	ds_read_b32 v0, v85 offset:224
	ds_read_b32 v2, v85 offset:484
	ds_read_b32 v3, v85 offset:744
	ds_read_b32 v4, v85 offset:1004
	ds_read_b32 v5, v85 offset:1264
	ds_read_b32 v8, v85 offset:1524
	ds_read_b32 v9, v85 offset:1784
	ds_read_b32 v10, v85 offset:2044
	s_waitcnt lgkmcnt(0)
	v_cvt_pk_bf16_f32 v2, v0, v2
	v_or_b32_e32 v0, s25, v92
	v_lshlrev_b32_e32 v0, 12, v0
	v_lshl_add_u64 v[6:7], v[6:7], 0, v[0:1]
	v_cvt_pk_bf16_f32 v3, v3, v4
	v_cvt_pk_bf16_f32 v4, v5, v8
	v_cvt_pk_bf16_f32 v5, v9, v10
	flat_store_dwordx4 v[6:7], v[2:5] sc1
	s_waitcnt lgkmcnt(0)

; #define LAS __attribute__((address_space(3)))
; __device__ __forceinline__ unsigned cvt_pk_bf16(float lo, float hi) { unsigned r; asm("v_cvt_pk_bf16_f32 %0, %1, %2" : "=v"(r) : "v"(lo), "v"(hi)); return r; }
; template <int MAPK>
; __device__ __forceinline__ void transpose_item(const float* W, int K, int N, int ND, bf16_t* WT, const float* g, LAS float* scr, int item, int lane) {
;     ...
;     for (int i = 0; i < 16; ++i) { const int kk = 4 * i + kr; f32x4 v = vv[i];
;         if (g) v = v * g[k0 + kk];
;         scr[kk * 65 + c4] = v[0]; scr[kk * 65 + c4 + 1] = v[1]; scr[kk * 65 + c4 + 2] = v[2]; scr[kk * 65 + c4 + 3] = v[3]; }
;     asm volatile("s_waitcnt lgkmcnt(0)" ::: "memory");
;     const int c = lane & 7;
; #pragma unroll
;     for (int j = 0; j < 8; ++j) { const int n = (lane >> 3) + 8 * j; const LAS float* sp = scr + (8 * c) * 65 + n;
;         u32x4 o; o.x = cvt_pk_bf16(sp[0], sp[65]); o.y = cvt_pk_bf16(sp[2 * 65], sp[3 * 65]); o.z = cvt_pk_bf16(sp[4 * 65], sp[5 * 65]); o.w = cvt_pk_bf16(sp[6 * 65], sp[7 * 65]);
;         *(u32x4*)(WT + (size_t)(n0 + n) * K + k0 + 8 * c) = o; }
;     asm volatile("s_waitcnt lgkmcnt(0)" ::: "memory");
.LBB0_112:
	v_add_u32_e32 v0, 0x1040, v34
	ds_write2_b32 v0, v16, v17 offset1:1
	v_add_u32_e32 v0, 0x1048, v34
	ds_write2_b32 v0, v14, v15 offset1:1
	v_add_u32_e32 v0, 0x1450, v34
	s_add_u32 s0, s7, s91
	ds_write2_b32 v0, v10, v11 offset1:1
	v_add_u32_e32 v0, 0x1458, v34
	s_addc_u32 s1, s9, s90
	ds_write2_b32 v0, v12, v13 offset1:1
	s_lshl_b32 s20, s92, 1
	s_waitcnt lgkmcnt(0)
	s_add_u32 s0, s0, s20
	s_addc_u32 s1, s1, 0
	v_mov_b32_e32 v79, v1
	ds_read_b32 v0, v85
	ds_read_b32 v4, v85 offset:260
	ds_read_b32 v5, v85 offset:520
	ds_read_b32 v8, v85 offset:780
	ds_read_b32 v9, v85 offset:1040
	ds_read_b32 v10, v85 offset:1300
	ds_read_b32 v11, v85 offset:1560
	ds_read_b32 v12, v85 offset:1820
	v_lshl_add_u64 v[2:3], s[0:1], 0, v[78:79]
	s_mov_b64 s[0:1], 0x1b00000
	v_lshl_add_u64 v[6:7], v[2:3], 0, s[0:1]
	s_waitcnt lgkmcnt(0)
	v_cvt_pk_bf16_f32 v2, v0, v4
	v_or_b32_e32 v0, s25, v84
	v_lshlrev_b32_e32 v0, 12, v0
	v_cvt_pk_bf16_f32 v3, v5, v8
	v_cvt_pk_bf16_f32 v4, v9, v10
	v_lshl_add_u64 v[8:9], v[6:7], 0, v[0:1]
	v_cvt_pk_bf16_f32 v5, v11, v12
	flat_store_dwordx4 v[8:9], v[2:5] sc1
	ds_read_b32 v0, v85 offset:32
	ds_read_b32 v2, v85 offset:292
	ds_read_b32 v3, v85 offset:552
	ds_read_b32 v4, v85 offset:812
	ds_read_b32 v5, v85 offset:1072
	ds_read_b32 v8, v85 offset:1332
	ds_read_b32 v9, v85 offset:1592
	ds_read_b32 v10, v85 offset:1852
	s_waitcnt lgkmcnt(0)
	v_cvt_pk_bf16_f32 v2, v0, v2
	v_or_b32_e32 v0, s25, v86
	v_lshlrev_b32_e32 v0, 12, v0
	v_cvt_pk_bf16_f32 v3, v3, v4
	v_cvt_pk_bf16_f32 v4, v5, v8
	v_cvt_pk_bf16_f32 v5, v9, v10
	v_lshl_add_u64 v[8:9], v[6:7], 0, v[0:1]
	flat_store_dwordx4 v[8:9], v[2:5] sc1
	ds_read_b32 v0, v85 offset:64
	ds_read_b32 v2, v85 offset:324
	ds_read_b32 v3, v85 offset:584
	ds_read_b32 v4, v85 offset:844
	ds_read_b32 v5, v85 offset:1104
	ds_read_b32 v8, v85 offset:1364
	ds_read_b32 v9, v85 offset:1624
	ds_read_b32 v10, v85 offset:1884
	s_waitcnt lgkmcnt(0)
	v_cvt_pk_bf16_f32 v2, v0, v2
	v_or_b32_e32 v0, s25, v87
	v_lshlrev_b32_e32 v0, 12, v0
	v_cvt_pk_bf16_f32 v3, v3, v4
	v_cvt_pk_bf16_f32 v4, v5, v8
	v_cvt_pk_bf16_f32 v5, v9, v10
	v_lshl_add_u64 v[8:9], v[6:7], 0, v[0:1]
	flat_store_dwordx4 v[8:9], v[2:5] sc1
	ds_read_b32 v0, v85 offset:96
	ds_read_b32 v2, v85 offset:356
	ds_read_b32 v3, v85 offset:616
	ds_read_b32 v4, v85 offset:876
	ds_read_b32 v5, v85 offset:1136
	ds_read_b32 v8, v85 offset:1396
	ds_read_b32 v9, v85 offset:1656
	ds_read_b32 v10, v85 offset:1916
	s_waitcnt lgkmcnt(0)
	v_cvt_pk_bf16_f32 v2, v0, v2
	v_or_b32_e32 v0, s25, v88
	v_lshlrev_b32_e32 v0, 12, v0
	v_cvt_pk_bf16_f32 v3, v3, v4
	v_cvt_pk_bf16_f32 v4, v5, v8
	v_cvt_pk_bf16_f32 v5, v9, v10
	v_lshl_add_u64 v[8:9], v[6:7], 0, v[0:1]
	flat_store_dwordx4 v[8:9], v[2:5] sc1
	ds_read_b32 v0, v85 offset:128
	ds_read_b32 v2, v85 offset:388
	ds_read_b32 v3, v85 offset:648
	ds_read_b32 v4, v85 offset:908
	ds_read_b32 v5, v85 offset:1168
	ds_read_b32 v8, v85 offset:1428
	ds_read_b32 v9, v85 offset:1688
	ds_read_b32 v10, v85 offset:1948
	s_waitcnt lgkmcnt(0)
	v_cvt_pk_bf16_f32 v2, v0, v2
	v_or_b32_e32 v0, s25, v89
	v_lshlrev_b32_e32 v0, 12, v0
	v_cvt_pk_bf16_f32 v3, v3, v4
	v_cvt_pk_bf16_f32 v4, v5, v8
	v_cvt_pk_bf16_f32 v5, v9, v10
	v_lshl_add_u64 v[8:9], v[6:7], 0, v[0:1]
	flat_store_dwordx4 v[8:9], v[2:5] sc1
	ds_read_b32 v0, v85 offset:160
	ds_read_b32 v2, v85 offset:420
	ds_read_b32 v3, v85 offset:680
	ds_read_b32 v4, v85 offset:940
	ds_read_b32 v5, v85 offset:1200
	ds_read_b32 v8, v85 offset:1460
	ds_read_b32 v9, v85 offset:1720
	ds_read_b32 v10, v85 offset:1980
	s_waitcnt lgkmcnt(0)
	v_cvt_pk_bf16_f32 v2, v0, v2
	v_or_b32_e32 v0, s25, v90
	v_lshlrev_b32_e32 v0, 12, v0
	v_cvt_pk_bf16_f32 v3, v3, v4
	v_cvt_pk_bf16_f32 v4, v5, v8
	v_cvt_pk_bf16_f32 v5, v9, v10
	v_lshl_add_u64 v[8:9], v[6:7], 0, v[0:1]
	flat_store_dwordx4 v[8:9], v[2:5] sc1
	ds_read_b32 v0, v85 offset:192
	ds_read_b32 v2, v85 offset:452
	ds_read_b32 v3, v85 offset:712
	ds_read_b32 v4, v85 offset:972
	ds_read_b32 v5, v85 offset:1232
	ds_read_b32 v8, v85 offset:1492
	ds_read_b32 v9, v85 offset:1752
	ds_read_b32 v10, v85 offset:2012
	s_waitcnt lgkmcnt(0)
	v_cvt_pk_bf16_f32 v2, v0, v2
	v_or_b32_e32 v0, s25, v91
	v_lshlrev_b32_e32 v0, 12, v0
	v_cvt_pk_bf16_f32 v3, v3, v4
	v_cvt_pk_bf16_f32 v4, v5, v8
	v_cvt_pk_bf16_f32 v5, v9, v10
	v_lshl_add_u64 v[8:9], v[6:7], 0, v[0:1]
	flat_store_dwordx4 v[8:9], v[2:5] sc1
	ds_read_b32 v0, v85 offset:224
	ds_read_b32 v2, v85 offset:484
	ds_read_b32 v3, v85 offset:744
	ds_read_b32 v4, v85 offset:1004
	ds_read_b32 v5, v85 offset:1264
	ds_read_b32 v8, v85 offset:1524
	ds_read_b32 v9, v85 offset:1784
	ds_read_b32 v10, v85 offset:2044
	s_waitcnt lgkmcnt(0)
	v_cvt_pk_bf16_f32 v2, v0, v2
	v_or_b32_e32 v0, s25, v92
	v_lshlrev_b32_e32 v0, 12, v0
	v_lshl_add_u64 v[6:7], v[6:7], 0, v[0:1]
	v_cvt_pk_bf16_f32 v3, v3, v4
	v_cvt_pk_bf16_f32 v4, v5, v8
	v_cvt_pk_bf16_f32 v5, v9, v10
	flat_store_dwordx4 v[6:7], v[2:5] sc1
	s_waitcnt lgkmcnt(0)

; template <int MAPK>
; __device__ __forceinline__ void transpose_item(const float* W, int K, int N, int ND, bf16_t* WT, const float* g, LAS float* scr, int item, int lane) {
;     ...
;     const int c4 = (lane & 15) * 4, kr = lane >> 4;
;     int src = n0 + c4; if (MAPK == 1) src = inmap(src); if (MAPK == 2) src = upmap(src);
;     f32x4 vv[16];
; #pragma unroll
;     for (int i = 0; i < 16; ++i) { const int kk = 4 * i + kr;
;         vv[i] = (f32x4){0.f, 0.f, 0.f, 0.f};
;         if (src >= 0) vv[i] = *(const f32x4*)(W + (size_t)(k0 + kk) * N + src); }
; #pragma unroll
;     for (int i = 0; i < 16; ++i) { const int kk = 4 * i + kr; f32x4 v = vv[i];
;         if (g) v = v * g[k0 + kk];
;         scr[kk * 65 + c4] = v[0]; scr[kk * 65 + c4 + 1] = v[1]; scr[kk * 65 + c4 + 2] = v[2]; scr[kk * 65 + c4 + 3] = v[3]; }
; __global__ void __launch_bounds__(512, 2) hybrid_fwd(Params p) {
;     ...
;             if (r < I_OUT) { transpose_item<0>(p.w_mix_out + (size_t)l * D_ * D_, D_, D_, D_, (bf16_t*)(WL + OF_WOUT), nullptr, scr, r, lane); continue; } r -= I_OUT;
.LBB0_114:
	s_andn2_b64 vcc, exec, s[0:1]
	s_cbranch_vccnz .LBB0_116
	v_readlane_b32 s68, v255, 4
	s_lshl_b64 s[0:1], s[18:19], 24
	v_readlane_b32 s70, v255, 6
	v_readlane_b32 s71, v255, 7
	s_add_u32 s20, s70, s0
	s_addc_u32 s21, s71, s1
	s_add_u32 s1, s7, s91
	s_mul_i32 s0, s18, 0xffff9b00
	s_addc_u32 s19, s9, s90
	s_add_i32 s0, s30, s0
	s_add_i32 s0, s0, 0x1ed00
	s_and_b32 s22, s0, 0x1ffc0
	s_and_b32 s0, s28, 0x7c0
	v_or_b32_e32 v0, s0, v75
	v_or_b32_e32 v4, s22, v76
	v_lshlrev_b32_e32 v0, 2, v0
	v_lshl_add_u64 v[2:3], s[20:21], 0, v[0:1]
	v_lshlrev_b32_e32 v0, 13, v4
	v_lshl_add_u64 v[62:63], v[2:3], 0, v[0:1]
	v_add_co_u32_e32 v6, vcc, s96, v62
	s_mov_b32 s20, 0x70000
	s_nop 0
	v_addc_co_u32_e32 v7, vcc, 0, v63, vcc
	v_add_co_u32_e32 v10, vcc, s97, v62
	global_load_dwordx4 v[2:5], v[62:63], off
	s_nop 0
	global_load_dwordx4 v[6:9], v[6:7], off
	v_addc_co_u32_e32 v11, vcc, 0, v63, vcc
	v_add_co_u32_e32 v14, vcc, s10, v62
	v_mov_b32_e32 v79, v1
	s_nop 0
	v_addc_co_u32_e32 v15, vcc, 0, v63, vcc
	v_add_co_u32_e32 v18, vcc, s11, v62
	global_load_dwordx4 v[10:13], v[10:11], off
	s_nop 0
	global_load_dwordx4 v[14:17], v[14:15], off
	v_addc_co_u32_e32 v19, vcc, 0, v63, vcc
	v_add_co_u32_e32 v22, vcc, s85, v62
	v_readlane_b32 s69, v255, 5
	s_nop 0
	v_addc_co_u32_e32 v23, vcc, 0, v63, vcc
	v_add_co_u32_e32 v26, vcc, s86, v62
	global_load_dwordx4 v[18:21], v[18:19], off
	s_nop 0
	global_load_dwordx4 v[22:25], v[22:23], off
	v_addc_co_u32_e32 v27, vcc, 0, v63, vcc
	v_add_co_u32_e32 v30, vcc, s87, v62
	v_readlane_b32 s72, v255, 8
	s_nop 0
	v_addc_co_u32_e32 v31, vcc, 0, v63, vcc
	v_add_co_u32_e32 v34, vcc, s2, v62
	global_load_dwordx4 v[26:29], v[26:27], off
	s_nop 0
	global_load_dwordx4 v[30:33], v[30:31], off
	v_addc_co_u32_e32 v35, vcc, 0, v63, vcc
	v_add_co_u32_e32 v38, vcc, s3, v62
	v_readlane_b32 s73, v255, 9
	s_nop 0
	v_addc_co_u32_e32 v39, vcc, 0, v63, vcc
	v_add_co_u32_e32 v42, vcc, s12, v62
	global_load_dwordx4 v[34:37], v[34:35], off
	s_nop 0
	global_load_dwordx4 v[38:41], v[38:39], off
	v_addc_co_u32_e32 v43, vcc, 0, v63, vcc
	v_add_co_u32_e32 v46, vcc, s13, v62
	v_readlane_b32 s74, v255, 10
	s_nop 0
	v_addc_co_u32_e32 v47, vcc, 0, v63, vcc
	v_add_co_u32_e32 v50, vcc, s93, v62
	global_load_dwordx4 v[42:45], v[42:43], off
	s_nop 0
	global_load_dwordx4 v[46:49], v[46:47], off
	v_addc_co_u32_e32 v51, vcc, 0, v63, vcc
	v_add_co_u32_e32 v54, vcc, s94, v62
	v_readlane_b32 s75, v255, 11
	s_nop 0
	v_addc_co_u32_e32 v55, vcc, 0, v63, vcc
	global_load_dwordx4 v[50:53], v[50:51], off
	s_nop 0
	global_load_dwordx4 v[54:57], v[54:55], off
	v_add_co_u32_e32 v58, vcc, s20, v62
	s_lshl_b32 s20, s22, 1
	s_nop 0
	v_addc_co_u32_e32 v59, vcc, 0, v63, vcc
	global_load_dwordx4 v[58:61], v[58:59], off
	v_add_co_u32_e32 v62, vcc, s84, v62
	s_add_u32 s20, s1, s20
	s_nop 0
	v_addc_co_u32_e32 v63, vcc, 0, v63, vcc
	global_load_dwordx4 v[62:65], v[62:63], off
	s_addc_u32 s21, s19, 0
	v_readlane_b32 s76, v255, 12
	v_readlane_b32 s77, v255, 13
	v_readlane_b32 s78, v255, 14
	v_readlane_b32 s79, v255, 15
	v_readlane_b32 s80, v255, 16
	v_readlane_b32 s81, v255, 17
	v_readlane_b32 s82, v255, 18
	v_readlane_b32 s83, v255, 19
	s_waitcnt vmcnt(0)
	ds_write2_b32 v83, v2, v3 offset1:1
	ds_write2_b32 v83, v4, v5 offset0:2 offset1:3
	ds_write2_b32 v99, v6, v7 offset1:1
	ds_write2_b32 v100, v8, v9 offset1:1
	ds_write2_b32 v101, v10, v11 offset1:1
	ds_write2_b32 v102, v12, v13 offset1:1
	ds_write2_b32 v103, v14, v15 offset1:1
	ds_write2_b32 v104, v16, v17 offset1:1
	ds_write2_b32 v105, v18, v19 offset1:1
	ds_write2_b32 v106, v20, v21 offset1:1
	ds_write2_b32 v107, v22, v23 offset1:1
	ds_write2_b32 v108, v24, v25 offset1:1
	ds_write2_b32 v109, v26, v27 offset1:1
	ds_write2_b32 v110, v28, v29 offset1:1
	ds_write2_b32 v111, v30, v31 offset1:1
	ds_write2_b32 v112, v32, v33 offset1:1
	ds_write2_b32 v113, v34, v35 offset1:1
	ds_write2_b32 v114, v36, v37 offset1:1
	ds_write2_b32 v115, v38, v39 offset1:1
	ds_write2_b32 v116, v40, v41 offset1:1
	ds_write2_b32 v117, v42, v43 offset1:1
	ds_write2_b32 v118, v44, v45 offset1:1
	ds_write2_b32 v119, v46, v47 offset1:1
	ds_write2_b32 v120, v48, v49 offset1:1
	ds_write2_b32 v121, v50, v51 offset1:1
	ds_write2_b32 v122, v52, v53 offset1:1
	ds_write2_b32 v123, v54, v55 offset1:1
	ds_write2_b32 v124, v56, v57 offset1:1
	ds_write2_b32 v125, v58, v59 offset1:1
	ds_write2_b32 v126, v60, v61 offset1:1
	ds_write2_b32 v127, v62, v63 offset1:1
	ds_write2_b32 v128, v64, v65 offset1:1
	s_waitcnt lgkmcnt(0)
; #define LAS __attribute__((address_space(3)))
; __device__ __forceinline__ unsigned cvt_pk_bf16(float lo, float hi) { unsigned r; asm("v_cvt_pk_bf16_f32 %0, %1, %2" : "=v"(r) : "v"(lo), "v"(hi)); return r; }
; template <int MAPK>
; __device__ __forceinline__ void transpose_item(const float* W, int K, int N, int ND, bf16_t* WT, const float* g, LAS float* scr, int item, int lane) {
;     ...
;     const int c = lane & 7;
; #pragma unroll
;     for (int j = 0; j < 8; ++j) { const int n = (lane >> 3) + 8 * j; const LAS float* sp = scr + (8 * c) * 65 + n;
;         u32x4 o; o.x = cvt_pk_bf16(sp[0], sp[65]); o.y = cvt_pk_bf16(sp[2 * 65], sp[3 * 65]); o.z = cvt_pk_bf16(sp[4 * 65], sp[5 * 65]); o.w = cvt_pk_bf16(sp[6 * 65], sp[7 * 65]);
;         *(u32x4*)(WT + (size_t)(n0 + n) * K + k0 + 8 * c) = o; }
	ds_read_b32 v0, v85
	ds_read_b32 v4, v85 offset:260
	ds_read_b32 v5, v85 offset:520
	ds_read_b32 v8, v85 offset:780
	ds_read_b32 v9, v85 offset:1040
	ds_read_b32 v10, v85 offset:1300
	ds_read_b32 v11, v85 offset:1560
	ds_read_b32 v12, v85 offset:1820
	v_lshl_add_u64 v[2:3], s[20:21], 0, v[78:79]
	s_mov_b64 s[20:21], 0x1300000
	v_lshl_add_u64 v[6:7], v[2:3], 0, s[20:21]
	s_waitcnt lgkmcnt(0)
	v_cvt_pk_bf16_f32 v2, v0, v4
	v_or_b32_e32 v0, s0, v84
	v_lshlrev_b32_e32 v0, 12, v0
	v_cvt_pk_bf16_f32 v3, v5, v8
	v_cvt_pk_bf16_f32 v4, v9, v10
	v_lshl_add_u64 v[8:9], v[6:7], 0, v[0:1]
	v_cvt_pk_bf16_f32 v5, v11, v12
	flat_store_dwordx4 v[8:9], v[2:5] sc1
	ds_read_b32 v0, v85 offset:32
	ds_read_b32 v2, v85 offset:292
	ds_read_b32 v3, v85 offset:552
	ds_read_b32 v4, v85 offset:812
	ds_read_b32 v5, v85 offset:1072
	ds_read_b32 v8, v85 offset:1332
	ds_read_b32 v9, v85 offset:1592
	ds_read_b32 v10, v85 offset:1852
	s_waitcnt lgkmcnt(0)
	v_cvt_pk_bf16_f32 v2, v0, v2
	v_or_b32_e32 v0, s0, v86
	v_lshlrev_b32_e32 v0, 12, v0
	v_cvt_pk_bf16_f32 v3, v3, v4
	v_cvt_pk_bf16_f32 v4, v5, v8
	v_cvt_pk_bf16_f32 v5, v9, v10
	v_lshl_add_u64 v[8:9], v[6:7], 0, v[0:1]
	flat_store_dwordx4 v[8:9], v[2:5] sc1
	ds_read_b32 v0, v85 offset:64
	ds_read_b32 v2, v85 offset:324
	ds_read_b32 v3, v85 offset:584
	ds_read_b32 v4, v85 offset:844
	ds_read_b32 v5, v85 offset:1104
	ds_read_b32 v8, v85 offset:1364
	ds_read_b32 v9, v85 offset:1624
	ds_read_b32 v10, v85 offset:1884
	s_waitcnt lgkmcnt(0)
	v_cvt_pk_bf16_f32 v2, v0, v2
	v_or_b32_e32 v0, s0, v87
	v_lshlrev_b32_e32 v0, 12, v0
	v_cvt_pk_bf16_f32 v3, v3, v4
	v_cvt_pk_bf16_f32 v4, v5, v8
	v_cvt_pk_bf16_f32 v5, v9, v10
	v_lshl_add_u64 v[8:9], v[6:7], 0, v[0:1]
	flat_store_dwordx4 v[8:9], v[2:5] sc1
	ds_read_b32 v0, v85 offset:96
	ds_read_b32 v2, v85 offset:356
	ds_read_b32 v3, v85 offset:616
	ds_read_b32 v4, v85 offset:876
	ds_read_b32 v5, v85 offset:1136
	ds_read_b32 v8, v85 offset:1396
	ds_read_b32 v9, v85 offset:1656
	ds_read_b32 v10, v85 offset:1916
	s_waitcnt lgkmcnt(0)
	v_cvt_pk_bf16_f32 v2, v0, v2
	v_or_b32_e32 v0, s0, v88
	v_lshlrev_b32_e32 v0, 12, v0
	v_cvt_pk_bf16_f32 v3, v3, v4
	v_cvt_pk_bf16_f32 v4, v5, v8
	v_cvt_pk_bf16_f32 v5, v9, v10
	v_lshl_add_u64 v[8:9], v[6:7], 0, v[0:1]
	flat_store_dwordx4 v[8:9], v[2:5] sc1
	ds_read_b32 v0, v85 offset:128
	ds_read_b32 v2, v85 offset:388
	ds_read_b32 v3, v85 offset:648
	ds_read_b32 v4, v85 offset:908
	ds_read_b32 v5, v85 offset:1168
	ds_read_b32 v8, v85 offset:1428
	ds_read_b32 v9, v85 offset:1688
	ds_read_b32 v10, v85 offset:1948
	s_waitcnt lgkmcnt(0)
	v_cvt_pk_bf16_f32 v2, v0, v2
	v_or_b32_e32 v0, s0, v89
	v_lshlrev_b32_e32 v0, 12, v0
	v_cvt_pk_bf16_f32 v3, v3, v4
	v_cvt_pk_bf16_f32 v4, v5, v8
	v_cvt_pk_bf16_f32 v5, v9, v10
	v_lshl_add_u64 v[8:9], v[6:7], 0, v[0:1]
	flat_store_dwordx4 v[8:9], v[2:5] sc1
	ds_read_b32 v0, v85 offset:160
	ds_read_b32 v2, v85 offset:420
	ds_read_b32 v3, v85 offset:680
	ds_read_b32 v4, v85 offset:940
	ds_read_b32 v5, v85 offset:1200
	ds_read_b32 v8, v85 offset:1460
	ds_read_b32 v9, v85 offset:1720
	ds_read_b32 v10, v85 offset:1980
	s_waitcnt lgkmcnt(0)
	v_cvt_pk_bf16_f32 v2, v0, v2
	v_or_b32_e32 v0, s0, v90
	v_lshlrev_b32_e32 v0, 12, v0
	v_cvt_pk_bf16_f32 v3, v3, v4
	v_cvt_pk_bf16_f32 v4, v5, v8
	v_cvt_pk_bf16_f32 v5, v9, v10
	v_lshl_add_u64 v[8:9], v[6:7], 0, v[0:1]
	flat_store_dwordx4 v[8:9], v[2:5] sc1
	ds_read_b32 v0, v85 offset:192
	ds_read_b32 v2, v85 offset:452
	ds_read_b32 v3, v85 offset:712
	ds_read_b32 v4, v85 offset:972
	ds_read_b32 v5, v85 offset:1232
	ds_read_b32 v8, v85 offset:1492
	ds_read_b32 v9, v85 offset:1752
	ds_read_b32 v10, v85 offset:2012
	s_waitcnt lgkmcnt(0)
	v_cvt_pk_bf16_f32 v2, v0, v2
	v_or_b32_e32 v0, s0, v91
	v_lshlrev_b32_e32 v0, 12, v0
	v_cvt_pk_bf16_f32 v3, v3, v4
	v_cvt_pk_bf16_f32 v4, v5, v8
	v_cvt_pk_bf16_f32 v5, v9, v10
	v_lshl_add_u64 v[8:9], v[6:7], 0, v[0:1]
	flat_store_dwordx4 v[8:9], v[2:5] sc1
	ds_read_b32 v0, v85 offset:224
	ds_read_b32 v2, v85 offset:484
	ds_read_b32 v3, v85 offset:744
	ds_read_b32 v4, v85 offset:1004
	ds_read_b32 v5, v85 offset:1264
	ds_read_b32 v8, v85 offset:1524
	ds_read_b32 v9, v85 offset:1784
	ds_read_b32 v10, v85 offset:2044
	s_waitcnt lgkmcnt(0)
	v_cvt_pk_bf16_f32 v2, v0, v2
	v_or_b32_e32 v0, s0, v92
	v_lshlrev_b32_e32 v0, 12, v0
	v_lshl_add_u64 v[6:7], v[6:7], 0, v[0:1]
	v_cvt_pk_bf16_f32 v3, v3, v4
	v_cvt_pk_bf16_f32 v4, v5, v8
	v_cvt_pk_bf16_f32 v5, v9, v10
	flat_store_dwordx4 v[6:7], v[2:5] sc1
	s_waitcnt lgkmcnt(0)

; __device__ __forceinline__ unsigned cvt_pk_bf16(float lo, float hi) { unsigned r; asm("v_cvt_pk_bf16_f32 %0, %1, %2" : "=v"(r) : "v"(lo), "v"(hi)); return r; }
; __global__ void __launch_bounds__(512, 2) hybrid_fwd(Params p) {
;     ...
;         for (int mrow = gw; mrow < T_ + MEM_; mrow += NGW) {
;             const bool ism = mrow >= T_; const float* src = ism ? p.mem + (size_t)(mrow - T_) * D_ : p.x + (size_t)mrow * D_;
;             bf16_t* dst = ism ? MEMB + (size_t)(mrow - T_) * D_ : HB + (size_t)mrow * D_;
;             f32x4 v[8]; float s = 0.f;
; #pragma unroll
;             for (int j = 0; j < 8; ++j) { v[j] = *(const f32x4*)(src + 256 * j + 4 * lane); s += (v[j][0] * v[j][0] + v[j][1] * v[j][1]) + (v[j][2] * v[j][2] + v[j][3] * v[j][3]); }
;             s = wave_sum(s, lane);
;             float sc = 1.f; if (ism) sc = rsqrtf(s * (1.f / D_) + EPS); else if (lane == 0) ssq[mrow] = (u64)__float2ull_rn(s * SSQ_SCALE);
; #pragma unroll
;             for (int j = 0; j < 8; ++j) { u32x2 w2; w2.x = cvt_pk_bf16(v[j][0] * sc, v[j][1] * sc); w2.y = cvt_pk_bf16(v[j][2] * sc, v[j][3] * sc); *(u32x2*)(dst + 256 * j + 4 * lane) = w2; }
.LBB0_246:
	s_and_b64 s[16:17], s[16:17], exec
	s_cselect_b32 s16, s22, 0x1d600000
	s_add_u32 s16, s4, s16
	s_addc_u32 s17, s5, 0
	s_lshl_b64 s[14:15], s[14:15], 12
	s_add_u32 s14, s16, s14
	v_mul_f32_e32 v0, v43, v0
	v_mul_f32_e32 v1, v43, v1
	s_addc_u32 s15, s17, s15
	v_cvt_pk_bf16_f32 v0, v0, v1
	v_mul_f32_e32 v1, v43, v2
	v_lshl_add_u64 v[44:45], s[14:15], 0, v[34:35]
	v_mul_f32_e32 v2, v43, v3
	v_cvt_pk_bf16_f32 v1, v1, v2
	flat_store_dwordx2 v[44:45], v[0:1] offset:512 sc1
	v_mul_f32_e32 v0, v43, v4
	v_mul_f32_e32 v1, v43, v5
	v_cvt_pk_bf16_f32 v0, v0, v1
	v_mul_f32_e32 v1, v43, v6
	v_mul_f32_e32 v2, v43, v7
	v_cvt_pk_bf16_f32 v1, v1, v2
	flat_store_dwordx2 v[44:45], v[0:1] offset:1024 sc1
	v_mul_f32_e32 v0, v43, v8
	v_mul_f32_e32 v1, v43, v9
	v_cvt_pk_bf16_f32 v0, v0, v1
	v_mul_f32_e32 v1, v43, v10
	v_mul_f32_e32 v2, v43, v11
	v_cvt_pk_bf16_f32 v1, v1, v2
	flat_store_dwordx2 v[44:45], v[0:1] offset:1536 sc1
	v_mul_f32_e32 v0, v43, v16
	v_mul_f32_e32 v1, v43, v17
	v_cvt_pk_bf16_f32 v0, v0, v1
	v_mul_f32_e32 v1, v43, v18
	v_mul_f32_e32 v2, v43, v19
	v_cvt_pk_bf16_f32 v1, v1, v2
	flat_store_dwordx2 v[44:45], v[0:1] offset:2048 sc1
	v_mul_f32_e32 v0, v43, v20
	v_mul_f32_e32 v1, v43, v21
	v_cvt_pk_bf16_f32 v0, v0, v1
	v_mul_f32_e32 v1, v43, v22
	v_mul_f32_e32 v2, v43, v23
	v_cvt_pk_bf16_f32 v1, v1, v2
	flat_store_dwordx2 v[44:45], v[0:1] offset:2560 sc1
	v_mul_f32_e32 v0, v43, v24
	v_mul_f32_e32 v1, v43, v25
	s_add_u32 s6, s6, s8
	v_cvt_pk_bf16_f32 v0, v0, v1
	v_mul_f32_e32 v1, v43, v26
	s_addc_u32 s7, s7, s9
	v_mul_f32_e32 v2, v43, v27
	v_cvt_pk_bf16_f32 v1, v1, v2
	s_add_u32 s10, s10, s12
	v_mul_f32_e32 v12, v43, v12
	v_mul_f32_e32 v13, v43, v13
	flat_store_dwordx2 v[44:45], v[0:1] offset:3072 sc1
	v_mul_f32_e32 v0, v43, v28
	v_mul_f32_e32 v1, v43, v29
	s_addc_u32 s11, s11, s13
	v_cvt_pk_bf16_f32 v12, v12, v13
	v_mul_f32_e32 v13, v43, v14
	v_cvt_pk_bf16_f32 v0, v0, v1
	v_mul_f32_e32 v1, v43, v30
	s_cmpk_gt_i32 s6, 0x20ff
	v_mul_f32_e32 v14, v43, v15
	v_cvt_pk_bf16_f32 v13, v13, v14
	flat_store_dwordx2 v[44:45], v[12:13] sc1
	v_mul_f32_e32 v2, v43, v31
	v_cvt_pk_bf16_f32 v1, v1, v2
	flat_store_dwordx2 v[44:45], v[0:1] offset:3584 sc1
	s_cbranch_scc1 .LBB0_253
.LBB0_247:
	s_add_i32 s18, s6, 0xffffe000
	s_cmpk_gt_i32 s6, 0x1fff
	s_cselect_b64 s[16:17], -1, 0
	s_and_b64 s[14:15], s[16:17], exec
	s_cselect_b32 s15, 0, s7
	s_cselect_b32 s14, s18, s6
	s_cselect_b32 s23, s55, s53
	s_cselect_b32 s24, s54, s52
	s_lshl_b64 s[18:19], s[14:15], 13
	s_add_u32 s18, s24, s18
	s_addc_u32 s19, s23, s19
	global_load_dwordx4 v[12:15], v32, s[18:19]
	global_load_dwordx4 v[0:3], v32, s[18:19] offset:1024
	global_load_dwordx4 v[4:7], v32, s[18:19] offset:2048
	global_load_dwordx4 v[8:11], v32, s[18:19] offset:3072
	v_lshl_add_u64 v[16:17], s[18:19], 0, v[32:33]
	v_add_co_u32_e32 v28, vcc, s20, v16
	s_cmpk_lt_i32 s6, 0x2000
	s_nop 0
	v_addc_co_u32_e32 v29, vcc, 0, v17, vcc
	global_load_dwordx4 v[16:19], v[28:29], off
	global_load_dwordx4 v[20:23], v[28:29], off offset:1024
	global_load_dwordx4 v[24:27], v[28:29], off offset:2048
	s_nop 0
	global_load_dwordx4 v[28:31], v[28:29], off offset:3072
	s_mov_b64 s[18:19], -1
	s_waitcnt vmcnt(0)
	v_mul_f32_e32 v43, v13, v13
	v_mul_f32_e32 v44, v15, v15
	v_mul_f32_e32 v45, v1, v1
	v_mul_f32_e32 v46, v3, v3
	v_mul_f32_e32 v47, v5, v5
	v_mul_f32_e32 v48, v7, v7
	v_fmac_f32_e32 v43, v12, v12
	v_fmac_f32_e32 v44, v14, v14
	v_fmac_f32_e32 v45, v0, v0
	v_fmac_f32_e32 v46, v2, v2
	v_mul_f32_e32 v49, v9, v9
	v_mul_f32_e32 v50, v11, v11
	v_fmac_f32_e32 v47, v4, v4
	v_fmac_f32_e32 v48, v6, v6
	v_add_f32_e32 v43, v43, v44
	v_add_f32_e32 v44, v45, v46
	v_fmac_f32_e32 v49, v8, v8
	v_fmac_f32_e32 v50, v10, v10
	v_add_f32_e32 v45, v47, v48
	v_mul_f32_e32 v47, v17, v17
	v_mul_f32_e32 v48, v19, v19
	v_add_f32_e32 v43, v43, v44
	v_add_f32_e32 v46, v49, v50
	v_mul_f32_e32 v49, v21, v21
	v_mul_f32_e32 v50, v23, v23
	v_fmac_f32_e32 v47, v16, v16
	v_fmac_f32_e32 v48, v18, v18
	v_add_f32_e32 v43, v43, v45
	v_mul_f32_e32 v51, v25, v25
	v_mul_f32_e32 v52, v27, v27
	v_fmac_f32_e32 v49, v20, v20
	v_fmac_f32_e32 v50, v22, v22
	v_add_f32_e32 v44, v47, v48
	v_add_f32_e32 v43, v43, v46
	v_mul_f32_e32 v53, v29, v29
	v_mul_f32_e32 v54, v31, v31
	v_fmac_f32_e32 v51, v24, v24
	v_fmac_f32_e32 v52, v26, v26
	v_add_f32_e32 v45, v49, v50
	v_add_f32_e32 v43, v43, v44
	v_fmac_f32_e32 v53, v28, v28
	v_fmac_f32_e32 v54, v30, v30
	v_add_f32_e32 v47, v51, v52
	v_add_f32_e32 v43, v43, v45
	v_add_f32_e32 v48, v53, v54
	v_add_f32_e32 v43, v43, v47
	v_add_f32_e32 v43, v43, v48
	ds_bpermute_b32 v44, v36, v43
	s_waitcnt lgkmcnt(0)
	v_add_f32_e32 v43, v43, v44
	ds_bpermute_b32 v44, v37, v43
	s_waitcnt lgkmcnt(0)
	v_add_f32_e32 v43, v43, v44
	ds_bpermute_b32 v44, v38, v43
	s_waitcnt lgkmcnt(0)
	v_add_f32_e32 v43, v43, v44
	ds_bpermute_b32 v44, v39, v43
	s_waitcnt lgkmcnt(0)
	v_add_f32_e32 v43, v43, v44
	ds_bpermute_b32 v44, v40, v43
	s_waitcnt lgkmcnt(0)
	v_add_f32_e32 v43, v43, v44
	ds_bpermute_b32 v44, v41, v43
	s_waitcnt lgkmcnt(0)
	v_add_f32_e32 v44, v43, v44
	s_cbranch_scc0 .LBB0_251
	s_and_saveexec_b64 s[18:19], s[0:1]
	s_cbranch_execz .LBB0_250
	v_mul_f32_e32 v43, 0x4b800000, v44
	v_rndne_f32_e32 v43, v43
	v_mul_f32_e32 v45, 0x2f800000, v43
	v_floor_f32_e32 v45, v45
	v_fmac_f32_e32 v43, 0xcf800000, v45
	v_cvt_u32_f32_e32 v46, v43
	v_cvt_u32_f32_e32 v47, v45
	v_mov_b64_e32 v[48:49], s[10:11]
	flat_store_dwordx2 v[48:49], v[46:47] sc1

; __global__ void __launch_bounds__(512, 2) hybrid_fwd(Params p) {
;     ...
;         for (int i = c * 512 + tid; i < 12 * T_; i += G * 512) ssq[T_ + i] = 0ull;
.LBB0_255:
	v_add_u32_e32 v0, s6, v0
	v_cmp_lt_i32_e32 vcc, s7, v0
	flat_store_dwordx2 v[2:3], v[4:5] sc1
	s_or_b64 s[10:11], vcc, s[10:11]
	v_lshl_add_u64 v[2:3], v[2:3], 0, s[8:9]
	s_andn2_b64 exec, exec, s[10:11]
	s_cbranch_execnz .LBB0_255
